# K-loop main bodies too: s_setprio 0 moved behind the barrier that ends each MFMA segment (v20 had only done the peeled first trips)
# baseline (speedup 1.0000x reference)
.LBB0_176:
	s_add_u32 s14, s8, 0xfff80080
	s_addc_u32 s15, s9, -1
	s_add_i32 s91, 0, 0x10000
	s_cmp_eq_u32 s90, 28
	s_cselect_b32 s53, s11, s15
	s_cselect_b32 s52, s13, s14
	v_add_u32_e32 v14, s91, v188
	s_cselect_b32 s15, s57, s69
	s_cselect_b32 s14, s61, s68
	s_add_i32 s96, 0, 0x14000
	ds_read_b128 v[6:9], v14
	ds_read_b128 v[10:13], v14 offset:1024
	ds_read_b128 v[140:143], v14 offset:2048
	ds_read_b128 v[144:147], v14 offset:3072
	v_add_u32_e32 v14, s96, v188
	ds_read_b128 v[148:151], v14
	ds_read_b128 v[152:155], v14 offset:1024
	ds_read_b128 v[180:183], v14 offset:2048
	ds_read_b128 v[208:211], v14 offset:3072
	v_lshl_add_u64 v[14:15], s[8:9], 0, v[176:177]
	s_add_i32 m0, s40, 0xc000
	ds_read_b128 v[212:215], v206
	ds_read_b128 v[216:219], v206 offset:1024
	ds_read_b128 v[220:223], v206 offset:2048
	ds_read_b128 v[224:227], v206 offset:3072
	ds_read_b128 v[238:241], v206 offset:4096
	ds_read_b128 v[242:245], v206 offset:5120
	ds_read_b128 v[246:249], v206 offset:6144
	ds_read_b128 v[250:253], v206 offset:7168
	global_load_lds_dwordx4 v[14:15], off
	s_add_i32 m0, s40, 0xe000
	v_lshl_add_u64 v[14:15], s[8:9], 0, v[178:179]
	global_load_lds_dwordx4 v[14:15], off
	s_waitcnt vmcnt(8) lgkmcnt(0)
	s_setprio 1
	s_barrier
	v_mfma_f32_16x16x32_bf16 v[136:139], v[6:9], v[212:215], v[136:139]
	v_mfma_f32_16x16x32_bf16 v[104:107], v[140:143], v[212:215], v[104:107]
	v_mfma_f32_16x16x32_bf16 v[132:135], v[6:9], v[220:223], v[132:135]
	v_mfma_f32_16x16x32_bf16 v[100:103], v[140:143], v[220:223], v[100:103]
	v_mfma_f32_16x16x32_bf16 v[128:131], v[6:9], v[238:241], v[128:131]
	v_mfma_f32_16x16x32_bf16 v[96:99], v[140:143], v[238:241], v[96:99]
	v_mfma_f32_16x16x32_bf16 v[124:127], v[6:9], v[246:249], v[124:127]
	v_mfma_f32_16x16x32_bf16 v[92:95], v[140:143], v[246:249], v[92:95]
	v_mfma_f32_16x16x32_bf16 v[136:139], v[10:13], v[216:219], v[136:139]
	v_mfma_f32_16x16x32_bf16 v[104:107], v[144:147], v[216:219], v[104:107]
	v_mfma_f32_16x16x32_bf16 v[132:135], v[10:13], v[224:227], v[132:135]
	v_mfma_f32_16x16x32_bf16 v[100:103], v[144:147], v[224:227], v[100:103]
	v_mfma_f32_16x16x32_bf16 v[128:131], v[10:13], v[242:245], v[128:131]
	v_mfma_f32_16x16x32_bf16 v[96:99], v[144:147], v[242:245], v[96:99]
	v_mfma_f32_16x16x32_bf16 v[124:127], v[10:13], v[250:253], v[124:127]
	v_mfma_f32_16x16x32_bf16 v[92:95], v[144:147], v[250:253], v[92:95]
	s_setprio 0
	s_setprio 1
	v_mfma_f32_16x16x32_bf16 v[72:75], v[148:151], v[212:215], v[72:75]
	v_mfma_f32_16x16x32_bf16 v[40:43], v[180:183], v[212:215], v[40:43]
	v_mfma_f32_16x16x32_bf16 v[68:71], v[148:151], v[220:223], v[68:71]
	v_mfma_f32_16x16x32_bf16 v[36:39], v[180:183], v[220:223], v[36:39]
	v_mfma_f32_16x16x32_bf16 v[64:67], v[148:151], v[238:241], v[64:67]
	v_mfma_f32_16x16x32_bf16 v[32:35], v[180:183], v[238:241], v[32:35]
	v_mfma_f32_16x16x32_bf16 v[60:63], v[148:151], v[246:249], v[60:63]
	v_mfma_f32_16x16x32_bf16 v[28:31], v[180:183], v[246:249], v[28:31]
	v_mfma_f32_16x16x32_bf16 v[72:75], v[152:155], v[216:219], v[72:75]
	v_mfma_f32_16x16x32_bf16 v[40:43], v[208:211], v[216:219], v[40:43]
	v_mfma_f32_16x16x32_bf16 v[68:71], v[152:155], v[224:227], v[68:71]
	v_mfma_f32_16x16x32_bf16 v[36:39], v[208:211], v[224:227], v[36:39]
	v_mfma_f32_16x16x32_bf16 v[64:67], v[152:155], v[242:245], v[64:67]
	v_mfma_f32_16x16x32_bf16 v[32:35], v[208:211], v[242:245], v[32:35]
	v_mfma_f32_16x16x32_bf16 v[60:63], v[152:155], v[250:253], v[60:63]
	v_mfma_f32_16x16x32_bf16 v[28:31], v[208:211], v[250:253], v[28:31]
	s_barrier
	s_setprio 0
	s_add_i32 s91, s91, s33
	v_lshl_add_u64 v[156:157], s[14:15], 0, v[160:161]
	s_mov_b32 m0, s91
	ds_read_b128 v[212:215], v206 offset:16384
	ds_read_b128 v[216:219], v206 offset:17408
	ds_read_b128 v[220:223], v206 offset:18432
	ds_read_b128 v[224:227], v206 offset:19456
	ds_read_b128 v[238:241], v206 offset:20480
	ds_read_b128 v[242:245], v206 offset:21504
	ds_read_b128 v[246:249], v206 offset:22528
	ds_read_b128 v[250:253], v206 offset:23552
	global_load_lds_dwordx4 v[156:157], off
	s_add_i32 m0, s91, 0x2000
	s_add_u32 vcc_lo, s14, 0x80000
	v_lshl_add_u64 v[184:185], s[14:15], 0, v[164:165]
	s_addc_u32 vcc_hi, s15, 0
	s_add_i32 s91, s96, s33
	global_load_lds_dwordx4 v[184:185], off
	v_lshl_add_u64 v[14:15], vcc, 0, v[160:161]
	s_mov_b32 m0, s91
	v_lshl_add_u64 v[196:197], s[52:53], 0, v[158:159]
	global_load_lds_dwordx4 v[14:15], off
	v_lshl_add_u64 v[14:15], vcc, 0, v[164:165]
	s_add_i32 m0, s91, 0x2000
	v_lshl_add_u64 v[198:199], s[52:53], 0, v[162:163]
	global_load_lds_dwordx4 v[14:15], off
	s_mov_b32 m0, s40
	s_nop 0
	global_load_lds_dwordx4 v[196:197], off
	s_mov_b32 m0, s41
	s_nop 0
	global_load_lds_dwordx4 v[198:199], off
	s_waitcnt vmcnt(8) lgkmcnt(0)
	s_setprio 1
	s_barrier
	v_mfma_f32_16x16x32_bf16 v[120:123], v[6:9], v[212:215], v[120:123]
	v_mfma_f32_16x16x32_bf16 v[88:91], v[140:143], v[212:215], v[88:91]
	v_mfma_f32_16x16x32_bf16 v[116:119], v[6:9], v[220:223], v[116:119]
	v_mfma_f32_16x16x32_bf16 v[84:87], v[140:143], v[220:223], v[84:87]
	v_mfma_f32_16x16x32_bf16 v[112:115], v[6:9], v[238:241], v[112:115]
	v_mfma_f32_16x16x32_bf16 v[80:83], v[140:143], v[238:241], v[80:83]
	v_mfma_f32_16x16x32_bf16 v[6:9], v[6:9], v[246:249], v[108:111]
	v_mfma_f32_16x16x32_bf16 v[120:123], v[10:13], v[216:219], v[120:123]
	v_mfma_f32_16x16x32_bf16 v[88:91], v[144:147], v[216:219], v[88:91]
	v_mfma_f32_16x16x32_bf16 v[116:119], v[10:13], v[224:227], v[116:119]
	v_mfma_f32_16x16x32_bf16 v[84:87], v[144:147], v[224:227], v[84:87]
	v_mfma_f32_16x16x32_bf16 v[112:115], v[10:13], v[242:245], v[112:115]
	v_mfma_f32_16x16x32_bf16 v[80:83], v[144:147], v[242:245], v[80:83]
	v_mfma_f32_16x16x32_bf16 v[6:9], v[10:13], v[250:253], v[6:9]
	v_mfma_f32_16x16x32_bf16 v[10:13], v[140:143], v[246:249], v[76:79]
	v_mfma_f32_16x16x32_bf16 v[10:13], v[144:147], v[250:253], v[10:13]
	s_setprio 0
	s_setprio 1
	v_mfma_f32_16x16x32_bf16 v[56:59], v[148:151], v[212:215], v[56:59]
	v_mfma_f32_16x16x32_bf16 v[24:27], v[180:183], v[212:215], v[24:27]
	v_mfma_f32_16x16x32_bf16 v[52:55], v[148:151], v[220:223], v[52:55]
	v_mfma_f32_16x16x32_bf16 v[20:23], v[180:183], v[220:223], v[20:23]
	v_mfma_f32_16x16x32_bf16 v[48:51], v[148:151], v[238:241], v[48:51]
	v_mfma_f32_16x16x32_bf16 v[14:17], v[180:183], v[238:241], v[16:19]
	v_mfma_f32_16x16x32_bf16 v[44:47], v[148:151], v[246:249], v[44:47]
	v_mfma_f32_16x16x32_bf16 v[2:5], v[180:183], v[246:249], v[2:5]
	v_mfma_f32_16x16x32_bf16 v[56:59], v[152:155], v[216:219], v[56:59]
	v_mfma_f32_16x16x32_bf16 v[24:27], v[208:211], v[216:219], v[24:27]
	v_mfma_f32_16x16x32_bf16 v[52:55], v[152:155], v[224:227], v[52:55]
	v_mfma_f32_16x16x32_bf16 v[20:23], v[208:211], v[224:227], v[20:23]
	v_mfma_f32_16x16x32_bf16 v[48:51], v[152:155], v[242:245], v[48:51]
	v_mfma_f32_16x16x32_bf16 v[14:17], v[208:211], v[242:245], v[14:17]
	v_mfma_f32_16x16x32_bf16 v[44:47], v[152:155], v[250:253], v[44:47]
	v_mfma_f32_16x16x32_bf16 v[2:5], v[208:211], v[250:253], v[2:5]
	s_barrier
	s_setprio 0
	s_add_i32 s91, 0, 0x18000
	v_add_u32_e32 v18, s91, v188
	s_add_i32 s96, 0, 0x1c000
	ds_read_b128 v[76:79], v18
	ds_read_b128 v[108:111], v18 offset:1024
	ds_read_b128 v[140:143], v18 offset:2048
	ds_read_b128 v[144:147], v18 offset:3072
	v_add_u32_e32 v18, s96, v188
	ds_read_b128 v[148:151], v18
	ds_read_b128 v[152:155], v18 offset:1024
	ds_read_b128 v[180:183], v18 offset:2048
	ds_read_b128 v[208:211], v18 offset:3072
	s_add_u32 s52, s52, 0x80000
	s_addc_u32 s53, s53, 0
	s_mov_b32 m0, s42
	v_lshl_add_u64 v[18:19], s[52:53], 0, v[158:159]
	ds_read_b128 v[212:215], v206 offset:32768
	ds_read_b128 v[216:219], v206 offset:33792
	ds_read_b128 v[220:223], v206 offset:34816
	ds_read_b128 v[224:227], v206 offset:35840
	ds_read_b128 v[238:241], v206 offset:36864
	ds_read_b128 v[242:245], v206 offset:37888
	ds_read_b128 v[246:249], v206 offset:38912
	ds_read_b128 v[250:253], v206 offset:39936
	global_load_lds_dwordx4 v[18:19], off
	s_mov_b32 m0, s43
	v_lshl_add_u64 v[18:19], s[52:53], 0, v[162:163]
	global_load_lds_dwordx4 v[18:19], off
	s_waitcnt vmcnt(8) lgkmcnt(0)
	s_setprio 1
	s_barrier
	v_mfma_f32_16x16x32_bf16 v[136:139], v[76:79], v[212:215], v[136:139]
	v_mfma_f32_16x16x32_bf16 v[104:107], v[140:143], v[212:215], v[104:107]
	v_mfma_f32_16x16x32_bf16 v[132:135], v[76:79], v[220:223], v[132:135]
	v_mfma_f32_16x16x32_bf16 v[100:103], v[140:143], v[220:223], v[100:103]
	v_mfma_f32_16x16x32_bf16 v[128:131], v[76:79], v[238:241], v[128:131]
	v_mfma_f32_16x16x32_bf16 v[96:99], v[140:143], v[238:241], v[96:99]
	v_mfma_f32_16x16x32_bf16 v[124:127], v[76:79], v[246:249], v[124:127]
	v_mfma_f32_16x16x32_bf16 v[92:95], v[140:143], v[246:249], v[92:95]
	v_mfma_f32_16x16x32_bf16 v[136:139], v[108:111], v[216:219], v[136:139]
	v_mfma_f32_16x16x32_bf16 v[104:107], v[144:147], v[216:219], v[104:107]
	v_mfma_f32_16x16x32_bf16 v[132:135], v[108:111], v[224:227], v[132:135]
	v_mfma_f32_16x16x32_bf16 v[100:103], v[144:147], v[224:227], v[100:103]
	v_mfma_f32_16x16x32_bf16 v[128:131], v[108:111], v[242:245], v[128:131]
	v_mfma_f32_16x16x32_bf16 v[96:99], v[144:147], v[242:245], v[96:99]
	v_mfma_f32_16x16x32_bf16 v[124:127], v[108:111], v[250:253], v[124:127]
	v_mfma_f32_16x16x32_bf16 v[92:95], v[144:147], v[250:253], v[92:95]
	s_setprio 0
	s_setprio 1
	v_mfma_f32_16x16x32_bf16 v[72:75], v[148:151], v[212:215], v[72:75]
	v_mfma_f32_16x16x32_bf16 v[40:43], v[180:183], v[212:215], v[40:43]
	v_mfma_f32_16x16x32_bf16 v[68:71], v[148:151], v[220:223], v[68:71]
	v_mfma_f32_16x16x32_bf16 v[36:39], v[180:183], v[220:223], v[36:39]
	v_mfma_f32_16x16x32_bf16 v[64:67], v[148:151], v[238:241], v[64:67]
	v_mfma_f32_16x16x32_bf16 v[32:35], v[180:183], v[238:241], v[32:35]
	v_mfma_f32_16x16x32_bf16 v[60:63], v[148:151], v[246:249], v[60:63]
	v_mfma_f32_16x16x32_bf16 v[28:31], v[180:183], v[246:249], v[28:31]
	v_mfma_f32_16x16x32_bf16 v[72:75], v[152:155], v[216:219], v[72:75]
	v_mfma_f32_16x16x32_bf16 v[40:43], v[208:211], v[216:219], v[40:43]
	v_mfma_f32_16x16x32_bf16 v[68:71], v[152:155], v[224:227], v[68:71]
	v_mfma_f32_16x16x32_bf16 v[36:39], v[208:211], v[224:227], v[36:39]
	v_mfma_f32_16x16x32_bf16 v[64:67], v[152:155], v[242:245], v[64:67]
	v_mfma_f32_16x16x32_bf16 v[32:35], v[208:211], v[242:245], v[32:35]
	v_mfma_f32_16x16x32_bf16 v[60:63], v[152:155], v[250:253], v[60:63]
	v_mfma_f32_16x16x32_bf16 v[28:31], v[208:211], v[250:253], v[28:31]
	s_barrier
	s_setprio 0
	s_add_i32 s52, s91, s33
	v_lshl_add_u64 v[18:19], v[156:157], 0, s[58:59]
	s_mov_b32 m0, s52
	ds_read_b128 v[212:215], v206 offset:49152
	ds_read_b128 v[216:219], v206 offset:50176
	ds_read_b128 v[220:223], v206 offset:51200
	ds_read_b128 v[224:227], v206 offset:52224
	ds_read_b128 v[238:241], v206 offset:53248
	ds_read_b128 v[242:245], v206 offset:54272
	ds_read_b128 v[246:249], v206 offset:55296
	ds_read_b128 v[250:253], v206 offset:56320
	global_load_lds_dwordx4 v[18:19], off
	s_add_i32 m0, s52, 0x2000
	s_add_u32 s14, s14, 0x80080
	v_lshl_add_u64 v[18:19], v[184:185], 0, s[58:59]
	s_addc_u32 s15, s15, 0
	s_add_i32 s52, s96, s33
	global_load_lds_dwordx4 v[18:19], off
	s_mov_b32 m0, s52
	v_lshl_add_u64 v[18:19], s[14:15], 0, v[160:161]
	global_load_lds_dwordx4 v[18:19], off
	s_add_i32 m0, s52, 0x2000
	v_lshl_add_u64 v[18:19], s[14:15], 0, v[164:165]
	global_load_lds_dwordx4 v[18:19], off
	s_mov_b32 m0, s55
	v_lshl_add_u64 v[18:19], v[196:197], 0, s[58:59]
	global_load_lds_dwordx4 v[18:19], off
	s_mov_b32 m0, s77
	v_lshl_add_u64 v[18:19], v[198:199], 0, s[58:59]
	global_load_lds_dwordx4 v[18:19], off
	s_waitcnt vmcnt(8) lgkmcnt(0)
	s_setprio 1
	s_barrier
	v_mfma_f32_16x16x32_bf16 v[120:123], v[76:79], v[212:215], v[120:123]
	v_mfma_f32_16x16x32_bf16 v[116:119], v[76:79], v[220:223], v[116:119]
	v_mfma_f32_16x16x32_bf16 v[112:115], v[76:79], v[238:241], v[112:115]
	v_mfma_f32_16x16x32_bf16 v[6:9], v[76:79], v[246:249], v[6:9]
	v_mfma_f32_16x16x32_bf16 v[120:123], v[108:111], v[216:219], v[120:123]
	v_mfma_f32_16x16x32_bf16 v[88:91], v[140:143], v[212:215], v[88:91]
	v_mfma_f32_16x16x32_bf16 v[116:119], v[108:111], v[224:227], v[116:119]
	v_mfma_f32_16x16x32_bf16 v[84:87], v[140:143], v[220:223], v[84:87]
	v_mfma_f32_16x16x32_bf16 v[112:115], v[108:111], v[242:245], v[112:115]
	v_mfma_f32_16x16x32_bf16 v[80:83], v[140:143], v[238:241], v[80:83]
	v_mfma_f32_16x16x32_bf16 v[108:111], v[108:111], v[250:253], v[6:9]
	v_mfma_f32_16x16x32_bf16 v[6:9], v[140:143], v[246:249], v[10:13]
	v_mfma_f32_16x16x32_bf16 v[88:91], v[144:147], v[216:219], v[88:91]
	v_mfma_f32_16x16x32_bf16 v[84:87], v[144:147], v[224:227], v[84:87]
	v_mfma_f32_16x16x32_bf16 v[80:83], v[144:147], v[242:245], v[80:83]
	v_mfma_f32_16x16x32_bf16 v[76:79], v[144:147], v[250:253], v[6:9]
	s_setprio 0
	s_setprio 1
	v_mfma_f32_16x16x32_bf16 v[6:9], v[148:151], v[212:215], v[56:59]
	v_mfma_f32_16x16x32_bf16 v[56:59], v[152:155], v[216:219], v[6:9]
	v_mfma_f32_16x16x32_bf16 v[6:9], v[180:183], v[212:215], v[24:27]
	v_mfma_f32_16x16x32_bf16 v[24:27], v[208:211], v[216:219], v[6:9]
	v_mfma_f32_16x16x32_bf16 v[6:9], v[148:151], v[220:223], v[52:55]
	v_mfma_f32_16x16x32_bf16 v[52:55], v[152:155], v[224:227], v[6:9]
	v_mfma_f32_16x16x32_bf16 v[6:9], v[180:183], v[220:223], v[20:23]
	v_mfma_f32_16x16x32_bf16 v[20:23], v[208:211], v[224:227], v[6:9]
	v_mfma_f32_16x16x32_bf16 v[6:9], v[148:151], v[238:241], v[48:51]
	v_mfma_f32_16x16x32_bf16 v[48:51], v[152:155], v[242:245], v[6:9]
	v_mfma_f32_16x16x32_bf16 v[6:9], v[180:183], v[238:241], v[14:17]
	v_mfma_f32_16x16x32_bf16 v[16:19], v[208:211], v[242:245], v[6:9]
	v_mfma_f32_16x16x32_bf16 v[6:9], v[148:151], v[246:249], v[44:47]
	v_mfma_f32_16x16x32_bf16 v[2:5], v[180:183], v[246:249], v[2:5]
	v_mfma_f32_16x16x32_bf16 v[44:47], v[152:155], v[250:253], v[6:9]
	v_mfma_f32_16x16x32_bf16 v[2:5], v[208:211], v[250:253], v[2:5]
	s_barrier
	s_setprio 0
	s_add_i32 s90, s90, 2
	s_add_u32 s8, s8, 0x100
	s_addc_u32 s9, s9, 0
	s_add_u32 s68, s68, 0x100
	s_addc_u32 s69, s69, 0
	s_cmp_gt_u32 s90, 29
	s_cbranch_scc0 .LBB0_176

.LBB0_672:
	s_add_u32 s24, s22, 0xfff80080
	s_addc_u32 s25, s23, -1
	s_add_i32 s41, 0, 0x10000
	s_cmp_eq_u32 s40, 28
	s_cselect_b32 s27, s11, s25
	s_cselect_b32 s26, s18, s24
	s_cselect_b32 s25, s9, s33
	s_cselect_b32 s24, s19, s21
	s_add_i32 s46, 0, 0x14000
	v_add_u32_e32 v142, s41, v214
	v_add_u32_e32 v158, s46, v214
	ds_read_b128 v[130:133], v142
	ds_read_b128 v[134:137], v142 offset:1024
	ds_read_b128 v[138:141], v142 offset:2048
	ds_read_b128 v[142:145], v142 offset:3072
	ds_read_b128 v[146:149], v158
	ds_read_b128 v[150:153], v158 offset:1024
	ds_read_b128 v[154:157], v158 offset:2048
	ds_read_b128 v[158:161], v158 offset:3072
	v_lshl_add_u64 v[212:213], s[22:23], 0, v[182:183]
	s_add_i32 m0, s17, 0xc000
	ds_read_b128 v[162:165], v216
	ds_read_b128 v[166:169], v216 offset:1024
	ds_read_b128 v[170:173], v216 offset:2048
	ds_read_b128 v[186:189], v216 offset:3072
	ds_read_b128 v[196:199], v216 offset:4096
	ds_read_b128 v[200:203], v216 offset:5120
	ds_read_b128 v[204:207], v216 offset:6144
	ds_read_b128 v[208:211], v216 offset:7168
	global_load_lds_dwordx4 v[212:213], off
	s_add_i32 m0, s17, 0xe000
	v_lshl_add_u64 v[212:213], s[22:23], 0, v[184:185]
	global_load_lds_dwordx4 v[212:213], off
	s_waitcnt vmcnt(8) lgkmcnt(0)
	s_setprio 1
	s_barrier
	v_mfma_f32_16x16x32_bf16 v[126:129], v[130:133], v[162:165], v[126:129]
	v_mfma_f32_16x16x32_bf16 v[122:125], v[138:141], v[162:165], v[122:125]
	v_mfma_f32_16x16x32_bf16 v[110:113], v[130:133], v[170:173], v[110:113]
	v_mfma_f32_16x16x32_bf16 v[106:109], v[138:141], v[170:173], v[106:109]
	v_mfma_f32_16x16x32_bf16 v[94:97], v[130:133], v[196:199], v[94:97]
	v_mfma_f32_16x16x32_bf16 v[90:93], v[138:141], v[196:199], v[90:93]
	v_mfma_f32_16x16x32_bf16 v[78:81], v[130:133], v[204:207], v[78:81]
	v_mfma_f32_16x16x32_bf16 v[74:77], v[138:141], v[204:207], v[74:77]
	v_mfma_f32_16x16x32_bf16 v[126:129], v[134:137], v[166:169], v[126:129]
	v_mfma_f32_16x16x32_bf16 v[122:125], v[142:145], v[166:169], v[122:125]
	v_mfma_f32_16x16x32_bf16 v[110:113], v[134:137], v[186:189], v[110:113]
	v_mfma_f32_16x16x32_bf16 v[106:109], v[142:145], v[186:189], v[106:109]
	v_mfma_f32_16x16x32_bf16 v[94:97], v[134:137], v[200:203], v[94:97]
	v_mfma_f32_16x16x32_bf16 v[90:93], v[142:145], v[200:203], v[90:93]
	v_mfma_f32_16x16x32_bf16 v[78:81], v[134:137], v[208:211], v[78:81]
	v_mfma_f32_16x16x32_bf16 v[74:77], v[142:145], v[208:211], v[74:77]
	s_setprio 0
	s_setprio 1
	v_mfma_f32_16x16x32_bf16 v[118:121], v[146:149], v[162:165], v[118:121]
	v_mfma_f32_16x16x32_bf16 v[114:117], v[154:157], v[162:165], v[114:117]
	v_mfma_f32_16x16x32_bf16 v[102:105], v[146:149], v[170:173], v[102:105]
	v_mfma_f32_16x16x32_bf16 v[98:101], v[154:157], v[170:173], v[98:101]
	v_mfma_f32_16x16x32_bf16 v[86:89], v[146:149], v[196:199], v[86:89]
	v_mfma_f32_16x16x32_bf16 v[82:85], v[154:157], v[196:199], v[82:85]
	v_mfma_f32_16x16x32_bf16 v[70:73], v[146:149], v[204:207], v[70:73]
	v_mfma_f32_16x16x32_bf16 v[66:69], v[154:157], v[204:207], v[66:69]
	v_mfma_f32_16x16x32_bf16 v[118:121], v[150:153], v[166:169], v[118:121]
	v_mfma_f32_16x16x32_bf16 v[114:117], v[158:161], v[166:169], v[114:117]
	v_mfma_f32_16x16x32_bf16 v[102:105], v[150:153], v[186:189], v[102:105]
	v_mfma_f32_16x16x32_bf16 v[98:101], v[158:161], v[186:189], v[98:101]
	v_mfma_f32_16x16x32_bf16 v[86:89], v[150:153], v[200:203], v[86:89]
	v_mfma_f32_16x16x32_bf16 v[82:85], v[158:161], v[200:203], v[82:85]
	v_mfma_f32_16x16x32_bf16 v[70:73], v[150:153], v[208:211], v[70:73]
	v_mfma_f32_16x16x32_bf16 v[66:69], v[158:161], v[208:211], v[66:69]
	s_barrier
	s_setprio 0
	s_add_i32 s41, s41, s29
	v_lshl_add_u64 v[212:213], s[24:25], 0, v[178:179]
	s_mov_b32 m0, s41
	ds_read_b128 v[162:165], v216 offset:16384
	ds_read_b128 v[166:169], v216 offset:17408
	ds_read_b128 v[170:173], v216 offset:18432
	ds_read_b128 v[186:189], v216 offset:19456
	ds_read_b128 v[196:199], v216 offset:20480
	ds_read_b128 v[200:203], v216 offset:21504
	ds_read_b128 v[204:207], v216 offset:22528
	ds_read_b128 v[208:211], v216 offset:23552
	global_load_lds_dwordx4 v[212:213], off
	s_add_i32 m0, s41, 0x2000
	s_add_u32 s42, s24, 0x80000
	v_lshl_add_u64 v[218:219], s[24:25], 0, v[174:175]
	s_addc_u32 s43, s25, 0
	s_add_i32 s41, s46, s29
	global_load_lds_dwordx4 v[218:219], off
	v_lshl_add_u64 v[220:221], s[42:43], 0, v[178:179]
	s_mov_b32 m0, s41
	v_lshl_add_u64 v[222:223], s[26:27], 0, v[176:177]
	global_load_lds_dwordx4 v[220:221], off
	s_add_i32 m0, s41, 0x2000
	v_lshl_add_u64 v[220:221], s[42:43], 0, v[174:175]
	global_load_lds_dwordx4 v[220:221], off
	s_mov_b32 m0, s17
	v_lshl_add_u64 v[220:221], s[26:27], 0, v[180:181]
	global_load_lds_dwordx4 v[220:221], off
	s_mov_b32 m0, s31
	s_nop 0
	global_load_lds_dwordx4 v[222:223], off
	s_waitcnt vmcnt(8) lgkmcnt(0)
	s_setprio 1
	s_barrier
	v_mfma_f32_16x16x32_bf16 v[62:65], v[130:133], v[162:165], v[62:65]
	v_mfma_f32_16x16x32_bf16 v[58:61], v[138:141], v[162:165], v[58:61]
	v_mfma_f32_16x16x32_bf16 v[46:49], v[130:133], v[170:173], v[46:49]
	v_mfma_f32_16x16x32_bf16 v[42:45], v[138:141], v[170:173], v[42:45]
	v_mfma_f32_16x16x32_bf16 v[30:33], v[130:133], v[196:199], v[30:33]
	v_mfma_f32_16x16x32_bf16 v[26:29], v[138:141], v[196:199], v[26:29]
	v_mfma_f32_16x16x32_bf16 v[14:17], v[130:133], v[204:207], v[14:17]
	v_mfma_f32_16x16x32_bf16 v[10:13], v[138:141], v[204:207], v[10:13]
	v_mfma_f32_16x16x32_bf16 v[62:65], v[134:137], v[166:169], v[62:65]
	v_mfma_f32_16x16x32_bf16 v[58:61], v[142:145], v[166:169], v[58:61]
	v_mfma_f32_16x16x32_bf16 v[46:49], v[134:137], v[186:189], v[46:49]
	v_mfma_f32_16x16x32_bf16 v[42:45], v[142:145], v[186:189], v[42:45]
	v_mfma_f32_16x16x32_bf16 v[30:33], v[134:137], v[200:203], v[30:33]
	v_mfma_f32_16x16x32_bf16 v[26:29], v[142:145], v[200:203], v[26:29]
	v_mfma_f32_16x16x32_bf16 v[14:17], v[134:137], v[208:211], v[14:17]
	v_mfma_f32_16x16x32_bf16 v[10:13], v[142:145], v[208:211], v[10:13]
	s_setprio 0
	s_setprio 1
	v_mfma_f32_16x16x32_bf16 v[54:57], v[146:149], v[162:165], v[54:57]
	v_mfma_f32_16x16x32_bf16 v[50:53], v[154:157], v[162:165], v[50:53]
	v_mfma_f32_16x16x32_bf16 v[38:41], v[146:149], v[170:173], v[38:41]
	v_mfma_f32_16x16x32_bf16 v[34:37], v[154:157], v[170:173], v[34:37]
	v_mfma_f32_16x16x32_bf16 v[22:25], v[146:149], v[196:199], v[22:25]
	v_mfma_f32_16x16x32_bf16 v[18:21], v[154:157], v[196:199], v[18:21]
	v_mfma_f32_16x16x32_bf16 v[6:9], v[146:149], v[204:207], v[6:9]
	v_mfma_f32_16x16x32_bf16 v[2:5], v[154:157], v[204:207], v[2:5]
	v_mfma_f32_16x16x32_bf16 v[54:57], v[150:153], v[166:169], v[54:57]
	v_mfma_f32_16x16x32_bf16 v[50:53], v[158:161], v[166:169], v[50:53]
	v_mfma_f32_16x16x32_bf16 v[38:41], v[150:153], v[186:189], v[38:41]
	v_mfma_f32_16x16x32_bf16 v[34:37], v[158:161], v[186:189], v[34:37]
	v_mfma_f32_16x16x32_bf16 v[22:25], v[150:153], v[200:203], v[22:25]
	v_mfma_f32_16x16x32_bf16 v[18:21], v[158:161], v[200:203], v[18:21]
	v_mfma_f32_16x16x32_bf16 v[6:9], v[150:153], v[208:211], v[6:9]
	v_mfma_f32_16x16x32_bf16 v[2:5], v[158:161], v[208:211], v[2:5]
	s_barrier
	s_setprio 0
	s_add_i32 s41, 0, 0x18000
	s_add_i32 s42, 0, 0x1c000
	v_add_u32_e32 v142, s41, v214
	v_add_u32_e32 v158, s42, v214
	ds_read_b128 v[130:133], v142
	ds_read_b128 v[134:137], v142 offset:1024
	ds_read_b128 v[138:141], v142 offset:2048
	ds_read_b128 v[142:145], v142 offset:3072
	ds_read_b128 v[146:149], v158
	ds_read_b128 v[150:153], v158 offset:1024
	ds_read_b128 v[154:157], v158 offset:2048
	ds_read_b128 v[158:161], v158 offset:3072
	s_add_u32 s26, s26, 0x80000
	s_addc_u32 s27, s27, 0
	s_mov_b32 m0, s34
	v_lshl_add_u64 v[224:225], s[26:27], 0, v[180:181]
	ds_read_b128 v[162:165], v216 offset:32768
	ds_read_b128 v[166:169], v216 offset:33792
	ds_read_b128 v[170:173], v216 offset:34816
	ds_read_b128 v[186:189], v216 offset:35840
	ds_read_b128 v[196:199], v216 offset:36864
	ds_read_b128 v[200:203], v216 offset:37888
	ds_read_b128 v[204:207], v216 offset:38912
	ds_read_b128 v[208:211], v216 offset:39936
	global_load_lds_dwordx4 v[224:225], off
	s_mov_b32 m0, s35
	v_lshl_add_u64 v[224:225], s[26:27], 0, v[176:177]
	global_load_lds_dwordx4 v[224:225], off
	s_waitcnt vmcnt(8) lgkmcnt(0)
	s_setprio 1
	s_barrier
	v_mfma_f32_16x16x32_bf16 v[126:129], v[130:133], v[162:165], v[126:129]
	v_mfma_f32_16x16x32_bf16 v[122:125], v[138:141], v[162:165], v[122:125]
	v_mfma_f32_16x16x32_bf16 v[110:113], v[130:133], v[170:173], v[110:113]
	v_mfma_f32_16x16x32_bf16 v[106:109], v[138:141], v[170:173], v[106:109]
	v_mfma_f32_16x16x32_bf16 v[94:97], v[130:133], v[196:199], v[94:97]
	v_mfma_f32_16x16x32_bf16 v[90:93], v[138:141], v[196:199], v[90:93]
	v_mfma_f32_16x16x32_bf16 v[78:81], v[130:133], v[204:207], v[78:81]
	v_mfma_f32_16x16x32_bf16 v[74:77], v[138:141], v[204:207], v[74:77]
	v_mfma_f32_16x16x32_bf16 v[126:129], v[134:137], v[166:169], v[126:129]
	v_mfma_f32_16x16x32_bf16 v[122:125], v[142:145], v[166:169], v[122:125]
	v_mfma_f32_16x16x32_bf16 v[110:113], v[134:137], v[186:189], v[110:113]
	v_mfma_f32_16x16x32_bf16 v[106:109], v[142:145], v[186:189], v[106:109]
	v_mfma_f32_16x16x32_bf16 v[94:97], v[134:137], v[200:203], v[94:97]
	v_mfma_f32_16x16x32_bf16 v[90:93], v[142:145], v[200:203], v[90:93]
	v_mfma_f32_16x16x32_bf16 v[78:81], v[134:137], v[208:211], v[78:81]
	v_mfma_f32_16x16x32_bf16 v[74:77], v[142:145], v[208:211], v[74:77]
	s_setprio 0
	s_setprio 1
	v_mfma_f32_16x16x32_bf16 v[118:121], v[146:149], v[162:165], v[118:121]
	v_mfma_f32_16x16x32_bf16 v[114:117], v[154:157], v[162:165], v[114:117]
	v_mfma_f32_16x16x32_bf16 v[102:105], v[146:149], v[170:173], v[102:105]
	v_mfma_f32_16x16x32_bf16 v[98:101], v[154:157], v[170:173], v[98:101]
	v_mfma_f32_16x16x32_bf16 v[86:89], v[146:149], v[196:199], v[86:89]
	v_mfma_f32_16x16x32_bf16 v[82:85], v[154:157], v[196:199], v[82:85]
	v_mfma_f32_16x16x32_bf16 v[70:73], v[146:149], v[204:207], v[70:73]
	v_mfma_f32_16x16x32_bf16 v[66:69], v[154:157], v[204:207], v[66:69]
	v_mfma_f32_16x16x32_bf16 v[118:121], v[150:153], v[166:169], v[118:121]
	v_mfma_f32_16x16x32_bf16 v[114:117], v[158:161], v[166:169], v[114:117]
	v_mfma_f32_16x16x32_bf16 v[102:105], v[150:153], v[186:189], v[102:105]
	v_mfma_f32_16x16x32_bf16 v[98:101], v[158:161], v[186:189], v[98:101]
	v_mfma_f32_16x16x32_bf16 v[86:89], v[150:153], v[200:203], v[86:89]
	v_mfma_f32_16x16x32_bf16 v[82:85], v[158:161], v[200:203], v[82:85]
	v_mfma_f32_16x16x32_bf16 v[70:73], v[150:153], v[208:211], v[70:73]
	v_mfma_f32_16x16x32_bf16 v[66:69], v[158:161], v[208:211], v[66:69]
	s_barrier
	s_setprio 0
	s_add_i32 s26, s41, s29
	v_lshl_add_u64 v[212:213], v[212:213], 0, s[58:59]
	s_mov_b32 m0, s26
	ds_read_b128 v[162:165], v216 offset:49152
	ds_read_b128 v[166:169], v216 offset:50176
	ds_read_b128 v[170:173], v216 offset:51200
	ds_read_b128 v[186:189], v216 offset:52224
	ds_read_b128 v[196:199], v216 offset:53248
	ds_read_b128 v[200:203], v216 offset:54272
	ds_read_b128 v[204:207], v216 offset:55296
	ds_read_b128 v[208:211], v216 offset:56320
	global_load_lds_dwordx4 v[212:213], off
	s_add_i32 m0, s26, 0x2000
	s_add_u32 s24, s24, 0x80080
	v_lshl_add_u64 v[212:213], v[218:219], 0, s[58:59]
	s_addc_u32 s25, s25, 0
	s_add_i32 s26, s42, s29
	global_load_lds_dwordx4 v[212:213], off
	s_mov_b32 m0, s26
	v_lshl_add_u64 v[212:213], s[24:25], 0, v[178:179]
	global_load_lds_dwordx4 v[212:213], off
	s_add_i32 m0, s26, 0x2000
	v_lshl_add_u64 v[212:213], s[24:25], 0, v[174:175]
	global_load_lds_dwordx4 v[212:213], off
	s_mov_b32 m0, s38
	v_lshl_add_u64 v[212:213], v[220:221], 0, s[58:59]
	global_load_lds_dwordx4 v[212:213], off
	s_mov_b32 m0, s39
	v_lshl_add_u64 v[212:213], v[222:223], 0, s[58:59]
	global_load_lds_dwordx4 v[212:213], off
	s_waitcnt vmcnt(8) lgkmcnt(0)
	s_setprio 1
	s_barrier
	v_mfma_f32_16x16x32_bf16 v[62:65], v[130:133], v[162:165], v[62:65]
	v_mfma_f32_16x16x32_bf16 v[58:61], v[138:141], v[162:165], v[58:61]
	v_mfma_f32_16x16x32_bf16 v[46:49], v[130:133], v[170:173], v[46:49]
	v_mfma_f32_16x16x32_bf16 v[42:45], v[138:141], v[170:173], v[42:45]
	v_mfma_f32_16x16x32_bf16 v[30:33], v[130:133], v[196:199], v[30:33]
	v_mfma_f32_16x16x32_bf16 v[26:29], v[138:141], v[196:199], v[26:29]
	v_mfma_f32_16x16x32_bf16 v[14:17], v[130:133], v[204:207], v[14:17]
	v_mfma_f32_16x16x32_bf16 v[10:13], v[138:141], v[204:207], v[10:13]
	v_mfma_f32_16x16x32_bf16 v[62:65], v[134:137], v[166:169], v[62:65]
	v_mfma_f32_16x16x32_bf16 v[58:61], v[142:145], v[166:169], v[58:61]
	v_mfma_f32_16x16x32_bf16 v[46:49], v[134:137], v[186:189], v[46:49]
	v_mfma_f32_16x16x32_bf16 v[42:45], v[142:145], v[186:189], v[42:45]
	v_mfma_f32_16x16x32_bf16 v[30:33], v[134:137], v[200:203], v[30:33]
	v_mfma_f32_16x16x32_bf16 v[26:29], v[142:145], v[200:203], v[26:29]
	v_mfma_f32_16x16x32_bf16 v[14:17], v[134:137], v[208:211], v[14:17]
	v_mfma_f32_16x16x32_bf16 v[10:13], v[142:145], v[208:211], v[10:13]
	s_setprio 0
	s_setprio 1
	v_mfma_f32_16x16x32_bf16 v[54:57], v[146:149], v[162:165], v[54:57]
	v_mfma_f32_16x16x32_bf16 v[50:53], v[154:157], v[162:165], v[50:53]
	v_mfma_f32_16x16x32_bf16 v[38:41], v[146:149], v[170:173], v[38:41]
	v_mfma_f32_16x16x32_bf16 v[34:37], v[154:157], v[170:173], v[34:37]
	v_mfma_f32_16x16x32_bf16 v[22:25], v[146:149], v[196:199], v[22:25]
	v_mfma_f32_16x16x32_bf16 v[18:21], v[154:157], v[196:199], v[18:21]
	v_mfma_f32_16x16x32_bf16 v[6:9], v[146:149], v[204:207], v[6:9]
	v_mfma_f32_16x16x32_bf16 v[2:5], v[154:157], v[204:207], v[2:5]
	v_mfma_f32_16x16x32_bf16 v[54:57], v[150:153], v[166:169], v[54:57]
	v_mfma_f32_16x16x32_bf16 v[50:53], v[158:161], v[166:169], v[50:53]
	v_mfma_f32_16x16x32_bf16 v[38:41], v[150:153], v[186:189], v[38:41]
	v_mfma_f32_16x16x32_bf16 v[34:37], v[158:161], v[186:189], v[34:37]
	v_mfma_f32_16x16x32_bf16 v[22:25], v[150:153], v[200:203], v[22:25]
	v_mfma_f32_16x16x32_bf16 v[18:21], v[158:161], v[200:203], v[18:21]
	v_mfma_f32_16x16x32_bf16 v[6:9], v[150:153], v[208:211], v[6:9]
	v_mfma_f32_16x16x32_bf16 v[2:5], v[158:161], v[208:211], v[2:5]
	s_barrier
	s_setprio 0
	s_add_i32 s40, s40, 2
	s_add_u32 s22, s22, 0x100
	s_addc_u32 s23, s23, 0
	s_add_u32 s21, s21, 0x100
	s_addc_u32 s33, s33, 0
	s_cmp_gt_u32 s40, 29
	s_cbranch_scc0 .LBB0_672

.LBB0_748:
	s_add_u32 s20, s16, 0xfff80080
	s_addc_u32 s21, s17, -1
	s_add_i32 s37, 0, 0x10000
	s_cmp_eq_u32 s36, 28
	s_cselect_b32 s23, s9, s21
	s_cselect_b32 s22, s31, s20
	s_cselect_b32 s21, s7, s35
	s_cselect_b32 s20, s33, s34
	s_add_i32 s40, 0, 0x14000
	v_add_u32_e32 v142, s37, v238
	v_add_u32_e32 v158, s40, v238
	ds_read_b128 v[130:133], v142
	ds_read_b128 v[134:137], v142 offset:1024
	ds_read_b128 v[138:141], v142 offset:2048
	ds_read_b128 v[142:145], v142 offset:3072
	ds_read_b128 v[146:149], v158
	ds_read_b128 v[150:153], v158 offset:1024
	ds_read_b128 v[154:157], v158 offset:2048
	ds_read_b128 v[158:161], v158 offset:3072
	v_lshl_add_u64 v[210:211], s[16:17], 0, v[206:207]
	s_add_i32 m0, s25, 0xc000
	ds_read_b128 v[162:165], v240
	ds_read_b128 v[166:169], v240 offset:1024
	ds_read_b128 v[170:173], v240 offset:2048
	ds_read_b128 v[174:177], v240 offset:3072
	ds_read_b128 v[178:181], v240 offset:4096
	ds_read_b128 v[182:185], v240 offset:5120
	ds_read_b128 v[186:189], v240 offset:6144
	ds_read_b128 v[196:199], v240 offset:7168
	global_load_lds_dwordx4 v[210:211], off
	s_add_i32 m0, s25, 0xe000
	v_lshl_add_u64 v[210:211], s[16:17], 0, v[208:209]
	global_load_lds_dwordx4 v[210:211], off
	s_waitcnt vmcnt(8) lgkmcnt(0)
	s_setprio 1
	s_barrier
	v_mfma_f32_16x16x32_bf16 v[126:129], v[130:133], v[162:165], v[126:129]
	v_mfma_f32_16x16x32_bf16 v[122:125], v[138:141], v[162:165], v[122:125]
	v_mfma_f32_16x16x32_bf16 v[110:113], v[130:133], v[170:173], v[110:113]
	v_mfma_f32_16x16x32_bf16 v[106:109], v[138:141], v[170:173], v[106:109]
	v_mfma_f32_16x16x32_bf16 v[98:101], v[130:133], v[178:181], v[98:101]
	v_mfma_f32_16x16x32_bf16 v[90:93], v[138:141], v[178:181], v[90:93]
	v_mfma_f32_16x16x32_bf16 v[82:85], v[130:133], v[186:189], v[82:85]
	v_mfma_f32_16x16x32_bf16 v[74:77], v[138:141], v[186:189], v[74:77]
	v_mfma_f32_16x16x32_bf16 v[126:129], v[134:137], v[166:169], v[126:129]
	v_mfma_f32_16x16x32_bf16 v[122:125], v[142:145], v[166:169], v[122:125]
	v_mfma_f32_16x16x32_bf16 v[110:113], v[134:137], v[174:177], v[110:113]
	v_mfma_f32_16x16x32_bf16 v[106:109], v[142:145], v[174:177], v[106:109]
	v_mfma_f32_16x16x32_bf16 v[98:101], v[134:137], v[182:185], v[98:101]
	v_mfma_f32_16x16x32_bf16 v[90:93], v[142:145], v[182:185], v[90:93]
	v_mfma_f32_16x16x32_bf16 v[82:85], v[134:137], v[196:199], v[82:85]
	v_mfma_f32_16x16x32_bf16 v[74:77], v[142:145], v[196:199], v[74:77]
	s_setprio 0
	s_setprio 1
	v_mfma_f32_16x16x32_bf16 v[118:121], v[146:149], v[162:165], v[118:121]
	v_mfma_f32_16x16x32_bf16 v[114:117], v[154:157], v[162:165], v[114:117]
	v_mfma_f32_16x16x32_bf16 v[102:105], v[146:149], v[170:173], v[102:105]
	v_mfma_f32_16x16x32_bf16 v[94:97], v[154:157], v[170:173], v[94:97]
	v_mfma_f32_16x16x32_bf16 v[86:89], v[146:149], v[178:181], v[86:89]
	v_mfma_f32_16x16x32_bf16 v[78:81], v[154:157], v[178:181], v[78:81]
	v_mfma_f32_16x16x32_bf16 v[70:73], v[146:149], v[186:189], v[70:73]
	v_mfma_f32_16x16x32_bf16 v[66:69], v[154:157], v[186:189], v[66:69]
	v_mfma_f32_16x16x32_bf16 v[118:121], v[150:153], v[166:169], v[118:121]
	v_mfma_f32_16x16x32_bf16 v[114:117], v[158:161], v[166:169], v[114:117]
	v_mfma_f32_16x16x32_bf16 v[102:105], v[150:153], v[174:177], v[102:105]
	v_mfma_f32_16x16x32_bf16 v[94:97], v[158:161], v[174:177], v[94:97]
	v_mfma_f32_16x16x32_bf16 v[86:89], v[150:153], v[182:185], v[86:89]
	v_mfma_f32_16x16x32_bf16 v[78:81], v[158:161], v[182:185], v[78:81]
	v_mfma_f32_16x16x32_bf16 v[70:73], v[150:153], v[196:199], v[70:73]
	v_mfma_f32_16x16x32_bf16 v[66:69], v[158:161], v[196:199], v[66:69]
	s_barrier
	s_setprio 0
	s_add_i32 s37, s37, s24
	v_lshl_add_u64 v[210:211], s[20:21], 0, v[190:191]
	s_mov_b32 m0, s37
	ds_read_b128 v[162:165], v240 offset:16384
	ds_read_b128 v[166:169], v240 offset:17408
	ds_read_b128 v[170:173], v240 offset:18432
	ds_read_b128 v[174:177], v240 offset:19456
	ds_read_b128 v[178:181], v240 offset:20480
	ds_read_b128 v[182:185], v240 offset:21504
	ds_read_b128 v[186:189], v240 offset:22528
	ds_read_b128 v[196:199], v240 offset:23552
	global_load_lds_dwordx4 v[210:211], off
	s_add_i32 m0, s37, 0x2000
	s_add_u32 s38, s20, 0x80000
	v_lshl_add_u64 v[212:213], s[20:21], 0, v[204:205]
	s_addc_u32 s39, s21, 0
	s_add_i32 s37, s40, s24
	global_load_lds_dwordx4 v[212:213], off
	v_lshl_add_u64 v[214:215], s[38:39], 0, v[190:191]
	s_mov_b32 m0, s37
	v_lshl_add_u64 v[216:217], s[22:23], 0, v[202:203]
	global_load_lds_dwordx4 v[214:215], off
	s_add_i32 m0, s37, 0x2000
	v_lshl_add_u64 v[214:215], s[38:39], 0, v[204:205]
	global_load_lds_dwordx4 v[214:215], off
	s_mov_b32 m0, s25
	v_lshl_add_u64 v[214:215], s[22:23], 0, v[200:201]
	global_load_lds_dwordx4 v[214:215], off
	s_mov_b32 m0, s26
	s_nop 0
	global_load_lds_dwordx4 v[216:217], off
	s_waitcnt vmcnt(8) lgkmcnt(0)
	s_setprio 1
	s_barrier
	v_mfma_f32_16x16x32_bf16 v[62:65], v[130:133], v[162:165], v[62:65]
	v_mfma_f32_16x16x32_bf16 v[58:61], v[138:141], v[162:165], v[58:61]
	v_mfma_f32_16x16x32_bf16 v[50:53], v[130:133], v[170:173], v[50:53]
	v_mfma_f32_16x16x32_bf16 v[42:45], v[138:141], v[170:173], v[42:45]
	v_mfma_f32_16x16x32_bf16 v[34:37], v[130:133], v[178:181], v[34:37]
	v_mfma_f32_16x16x32_bf16 v[26:29], v[138:141], v[178:181], v[26:29]
	v_mfma_f32_16x16x32_bf16 v[18:21], v[130:133], v[186:189], v[18:21]
	v_mfma_f32_16x16x32_bf16 v[10:13], v[138:141], v[186:189], v[10:13]
	v_mfma_f32_16x16x32_bf16 v[62:65], v[134:137], v[166:169], v[62:65]
	v_mfma_f32_16x16x32_bf16 v[58:61], v[142:145], v[166:169], v[58:61]
	v_mfma_f32_16x16x32_bf16 v[50:53], v[134:137], v[174:177], v[50:53]
	v_mfma_f32_16x16x32_bf16 v[42:45], v[142:145], v[174:177], v[42:45]
	v_mfma_f32_16x16x32_bf16 v[34:37], v[134:137], v[182:185], v[34:37]
	v_mfma_f32_16x16x32_bf16 v[26:29], v[142:145], v[182:185], v[26:29]
	v_mfma_f32_16x16x32_bf16 v[18:21], v[134:137], v[196:199], v[18:21]
	v_mfma_f32_16x16x32_bf16 v[10:13], v[142:145], v[196:199], v[10:13]
	s_setprio 0
	s_setprio 1
	v_mfma_f32_16x16x32_bf16 v[54:57], v[146:149], v[162:165], v[54:57]
	v_mfma_f32_16x16x32_bf16 v[46:49], v[154:157], v[162:165], v[46:49]
	v_mfma_f32_16x16x32_bf16 v[38:41], v[146:149], v[170:173], v[38:41]
	v_mfma_f32_16x16x32_bf16 v[30:33], v[154:157], v[170:173], v[30:33]
	v_mfma_f32_16x16x32_bf16 v[22:25], v[146:149], v[178:181], v[22:25]
	v_mfma_f32_16x16x32_bf16 v[14:17], v[154:157], v[178:181], v[14:17]
	v_mfma_f32_16x16x32_bf16 v[6:9], v[146:149], v[186:189], v[6:9]
	v_mfma_f32_16x16x32_bf16 v[2:5], v[154:157], v[186:189], v[2:5]
	v_mfma_f32_16x16x32_bf16 v[54:57], v[150:153], v[166:169], v[54:57]
	v_mfma_f32_16x16x32_bf16 v[46:49], v[158:161], v[166:169], v[46:49]
	v_mfma_f32_16x16x32_bf16 v[38:41], v[150:153], v[174:177], v[38:41]
	v_mfma_f32_16x16x32_bf16 v[30:33], v[158:161], v[174:177], v[30:33]
	v_mfma_f32_16x16x32_bf16 v[22:25], v[150:153], v[182:185], v[22:25]
	v_mfma_f32_16x16x32_bf16 v[14:17], v[158:161], v[182:185], v[14:17]
	v_mfma_f32_16x16x32_bf16 v[6:9], v[150:153], v[196:199], v[6:9]
	v_mfma_f32_16x16x32_bf16 v[2:5], v[158:161], v[196:199], v[2:5]
	s_barrier
	s_setprio 0
	s_add_i32 s37, 0, 0x18000
	s_add_i32 s38, 0, 0x1c000
	v_add_u32_e32 v142, s37, v238
	v_add_u32_e32 v158, s38, v238
	ds_read_b128 v[130:133], v142
	ds_read_b128 v[134:137], v142 offset:1024
	ds_read_b128 v[138:141], v142 offset:2048
	ds_read_b128 v[142:145], v142 offset:3072
	ds_read_b128 v[146:149], v158
	ds_read_b128 v[150:153], v158 offset:1024
	ds_read_b128 v[154:157], v158 offset:2048
	ds_read_b128 v[158:161], v158 offset:3072
	s_add_u32 s22, s22, 0x80000
	s_addc_u32 s23, s23, 0
	s_mov_b32 m0, s27
	v_lshl_add_u64 v[218:219], s[22:23], 0, v[200:201]
	ds_read_b128 v[162:165], v240 offset:32768
	ds_read_b128 v[166:169], v240 offset:33792
	ds_read_b128 v[170:173], v240 offset:34816
	ds_read_b128 v[174:177], v240 offset:35840
	ds_read_b128 v[178:181], v240 offset:36864
	ds_read_b128 v[182:185], v240 offset:37888
	ds_read_b128 v[186:189], v240 offset:38912
	ds_read_b128 v[196:199], v240 offset:39936
	global_load_lds_dwordx4 v[218:219], off
	s_mov_b32 m0, s28
	v_lshl_add_u64 v[218:219], s[22:23], 0, v[202:203]
	global_load_lds_dwordx4 v[218:219], off
	s_waitcnt vmcnt(8) lgkmcnt(0)
	s_setprio 1
	s_barrier
	v_mfma_f32_16x16x32_bf16 v[126:129], v[130:133], v[162:165], v[126:129]
	v_mfma_f32_16x16x32_bf16 v[122:125], v[138:141], v[162:165], v[122:125]
	v_mfma_f32_16x16x32_bf16 v[110:113], v[130:133], v[170:173], v[110:113]
	v_mfma_f32_16x16x32_bf16 v[106:109], v[138:141], v[170:173], v[106:109]
	v_mfma_f32_16x16x32_bf16 v[98:101], v[130:133], v[178:181], v[98:101]
	v_mfma_f32_16x16x32_bf16 v[90:93], v[138:141], v[178:181], v[90:93]
	v_mfma_f32_16x16x32_bf16 v[82:85], v[130:133], v[186:189], v[82:85]
	v_mfma_f32_16x16x32_bf16 v[74:77], v[138:141], v[186:189], v[74:77]
	v_mfma_f32_16x16x32_bf16 v[126:129], v[134:137], v[166:169], v[126:129]
	v_mfma_f32_16x16x32_bf16 v[122:125], v[142:145], v[166:169], v[122:125]
	v_mfma_f32_16x16x32_bf16 v[110:113], v[134:137], v[174:177], v[110:113]
	v_mfma_f32_16x16x32_bf16 v[106:109], v[142:145], v[174:177], v[106:109]
	v_mfma_f32_16x16x32_bf16 v[98:101], v[134:137], v[182:185], v[98:101]
	v_mfma_f32_16x16x32_bf16 v[90:93], v[142:145], v[182:185], v[90:93]
	v_mfma_f32_16x16x32_bf16 v[82:85], v[134:137], v[196:199], v[82:85]
	v_mfma_f32_16x16x32_bf16 v[74:77], v[142:145], v[196:199], v[74:77]
	s_setprio 0
	s_setprio 1
	v_mfma_f32_16x16x32_bf16 v[118:121], v[146:149], v[162:165], v[118:121]
	v_mfma_f32_16x16x32_bf16 v[114:117], v[154:157], v[162:165], v[114:117]
	v_mfma_f32_16x16x32_bf16 v[102:105], v[146:149], v[170:173], v[102:105]
	v_mfma_f32_16x16x32_bf16 v[94:97], v[154:157], v[170:173], v[94:97]
	v_mfma_f32_16x16x32_bf16 v[86:89], v[146:149], v[178:181], v[86:89]
	v_mfma_f32_16x16x32_bf16 v[78:81], v[154:157], v[178:181], v[78:81]
	v_mfma_f32_16x16x32_bf16 v[70:73], v[146:149], v[186:189], v[70:73]
	v_mfma_f32_16x16x32_bf16 v[66:69], v[154:157], v[186:189], v[66:69]
	v_mfma_f32_16x16x32_bf16 v[118:121], v[150:153], v[166:169], v[118:121]
	v_mfma_f32_16x16x32_bf16 v[114:117], v[158:161], v[166:169], v[114:117]
	v_mfma_f32_16x16x32_bf16 v[102:105], v[150:153], v[174:177], v[102:105]
	v_mfma_f32_16x16x32_bf16 v[94:97], v[158:161], v[174:177], v[94:97]
	v_mfma_f32_16x16x32_bf16 v[86:89], v[150:153], v[182:185], v[86:89]
	v_mfma_f32_16x16x32_bf16 v[78:81], v[158:161], v[182:185], v[78:81]
	v_mfma_f32_16x16x32_bf16 v[70:73], v[150:153], v[196:199], v[70:73]
	v_mfma_f32_16x16x32_bf16 v[66:69], v[158:161], v[196:199], v[66:69]
	s_barrier
	s_setprio 0
	s_add_i32 s22, s37, s24
	v_lshl_add_u64 v[210:211], v[210:211], 0, s[58:59]
	s_mov_b32 m0, s22
	ds_read_b128 v[162:165], v240 offset:49152
	ds_read_b128 v[166:169], v240 offset:50176
	ds_read_b128 v[170:173], v240 offset:51200
	ds_read_b128 v[174:177], v240 offset:52224
	ds_read_b128 v[178:181], v240 offset:53248
	ds_read_b128 v[182:185], v240 offset:54272
	ds_read_b128 v[186:189], v240 offset:55296
	ds_read_b128 v[196:199], v240 offset:56320
	global_load_lds_dwordx4 v[210:211], off
	s_add_i32 m0, s22, 0x2000
	s_add_u32 s20, s20, 0x80080
	v_lshl_add_u64 v[210:211], v[212:213], 0, s[58:59]
	s_addc_u32 s21, s21, 0
	s_add_i32 s22, s38, s24
	global_load_lds_dwordx4 v[210:211], off
	s_mov_b32 m0, s22
	v_lshl_add_u64 v[210:211], s[20:21], 0, v[190:191]
	global_load_lds_dwordx4 v[210:211], off
	s_add_i32 m0, s22, 0x2000
	v_lshl_add_u64 v[210:211], s[20:21], 0, v[204:205]
	global_load_lds_dwordx4 v[210:211], off
	s_mov_b32 m0, s29
	v_lshl_add_u64 v[210:211], v[214:215], 0, s[58:59]
	global_load_lds_dwordx4 v[210:211], off
	s_mov_b32 m0, s30
	v_lshl_add_u64 v[210:211], v[216:217], 0, s[58:59]
	global_load_lds_dwordx4 v[210:211], off
	s_waitcnt vmcnt(8) lgkmcnt(0)
	s_setprio 1
	s_barrier
	v_mfma_f32_16x16x32_bf16 v[62:65], v[130:133], v[162:165], v[62:65]
	v_mfma_f32_16x16x32_bf16 v[58:61], v[138:141], v[162:165], v[58:61]
	v_mfma_f32_16x16x32_bf16 v[50:53], v[130:133], v[170:173], v[50:53]
	v_mfma_f32_16x16x32_bf16 v[42:45], v[138:141], v[170:173], v[42:45]
	v_mfma_f32_16x16x32_bf16 v[34:37], v[130:133], v[178:181], v[34:37]
	v_mfma_f32_16x16x32_bf16 v[26:29], v[138:141], v[178:181], v[26:29]
	v_mfma_f32_16x16x32_bf16 v[18:21], v[130:133], v[186:189], v[18:21]
	v_mfma_f32_16x16x32_bf16 v[10:13], v[138:141], v[186:189], v[10:13]
	v_mfma_f32_16x16x32_bf16 v[62:65], v[134:137], v[166:169], v[62:65]
	v_mfma_f32_16x16x32_bf16 v[58:61], v[142:145], v[166:169], v[58:61]
	v_mfma_f32_16x16x32_bf16 v[50:53], v[134:137], v[174:177], v[50:53]
	v_mfma_f32_16x16x32_bf16 v[42:45], v[142:145], v[174:177], v[42:45]
	v_mfma_f32_16x16x32_bf16 v[34:37], v[134:137], v[182:185], v[34:37]
	v_mfma_f32_16x16x32_bf16 v[26:29], v[142:145], v[182:185], v[26:29]
	v_mfma_f32_16x16x32_bf16 v[18:21], v[134:137], v[196:199], v[18:21]
	v_mfma_f32_16x16x32_bf16 v[10:13], v[142:145], v[196:199], v[10:13]
	s_setprio 0
	s_setprio 1
	v_mfma_f32_16x16x32_bf16 v[54:57], v[146:149], v[162:165], v[54:57]
	v_mfma_f32_16x16x32_bf16 v[46:49], v[154:157], v[162:165], v[46:49]
	v_mfma_f32_16x16x32_bf16 v[38:41], v[146:149], v[170:173], v[38:41]
	v_mfma_f32_16x16x32_bf16 v[30:33], v[154:157], v[170:173], v[30:33]
	v_mfma_f32_16x16x32_bf16 v[22:25], v[146:149], v[178:181], v[22:25]
	v_mfma_f32_16x16x32_bf16 v[14:17], v[154:157], v[178:181], v[14:17]
	v_mfma_f32_16x16x32_bf16 v[6:9], v[146:149], v[186:189], v[6:9]
	v_mfma_f32_16x16x32_bf16 v[2:5], v[154:157], v[186:189], v[2:5]
	v_mfma_f32_16x16x32_bf16 v[54:57], v[150:153], v[166:169], v[54:57]
	v_mfma_f32_16x16x32_bf16 v[46:49], v[158:161], v[166:169], v[46:49]
	v_mfma_f32_16x16x32_bf16 v[38:41], v[150:153], v[174:177], v[38:41]
	v_mfma_f32_16x16x32_bf16 v[30:33], v[158:161], v[174:177], v[30:33]
	v_mfma_f32_16x16x32_bf16 v[22:25], v[150:153], v[182:185], v[22:25]
	v_mfma_f32_16x16x32_bf16 v[14:17], v[158:161], v[182:185], v[14:17]
	v_mfma_f32_16x16x32_bf16 v[6:9], v[150:153], v[196:199], v[6:9]
	v_mfma_f32_16x16x32_bf16 v[2:5], v[158:161], v[196:199], v[2:5]
	s_barrier
	s_setprio 0
	s_add_i32 s36, s36, 2
	s_add_u32 s16, s16, 0x100
	s_addc_u32 s17, s17, 0
	s_add_u32 s34, s34, 0x100
	s_addc_u32 s35, s35, 0
	s_cmp_gt_u32 s36, 29
	s_cbranch_scc0 .LBB0_748

.LBB0_772:
	s_add_u32 s28, s26, 0xfff80080
	s_addc_u32 s29, s27, -1
	s_add_i32 s47, 0, 0x10000
	s_cmp_eq_u32 s46, 28
	s_cselect_b32 s31, s17, s29
	s_cselect_b32 s30, s40, s28
	s_cselect_b32 s29, s15, s43
	s_cselect_b32 s28, s41, s42
	s_add_i32 s55, 0, 0x14000
	v_add_u32_e32 v142, s47, v220
	v_add_u32_e32 v158, s55, v220
	ds_read_b128 v[130:133], v142
	ds_read_b128 v[134:137], v142 offset:1024
	ds_read_b128 v[138:141], v142 offset:2048
	ds_read_b128 v[142:145], v142 offset:3072
	ds_read_b128 v[146:149], v158
	ds_read_b128 v[150:153], v158 offset:1024
	ds_read_b128 v[154:157], v158 offset:2048
	ds_read_b128 v[158:161], v158 offset:3072
	v_lshl_add_u64 v[210:211], s[26:27], 0, v[202:203]
	s_add_i32 m0, s34, 0xc000
	ds_read_b128 v[162:165], v222
	ds_read_b128 v[166:169], v222 offset:1024
	ds_read_b128 v[170:173], v222 offset:2048
	ds_read_b128 v[174:177], v222 offset:3072
	ds_read_b128 v[178:181], v222 offset:4096
	ds_read_b128 v[182:185], v222 offset:5120
	ds_read_b128 v[196:199], v222 offset:6144
	ds_read_b128 v[206:209], v222 offset:7168
	global_load_lds_dwordx4 v[210:211], off
	s_add_i32 m0, s34, 0xe000
	v_lshl_add_u64 v[210:211], s[26:27], 0, v[204:205]
	global_load_lds_dwordx4 v[210:211], off
	s_waitcnt vmcnt(8) lgkmcnt(0)
	s_setprio 1
	s_barrier
	v_mfma_f32_16x16x32_bf16 v[126:129], v[130:133], v[162:165], v[126:129]
	v_mfma_f32_16x16x32_bf16 v[122:125], v[138:141], v[162:165], v[122:125]
	v_mfma_f32_16x16x32_bf16 v[110:113], v[130:133], v[170:173], v[110:113]
	v_mfma_f32_16x16x32_bf16 v[106:109], v[138:141], v[170:173], v[106:109]
	v_mfma_f32_16x16x32_bf16 v[94:97], v[130:133], v[178:181], v[94:97]
	v_mfma_f32_16x16x32_bf16 v[90:93], v[138:141], v[178:181], v[90:93]
	v_mfma_f32_16x16x32_bf16 v[78:81], v[130:133], v[196:199], v[78:81]
	v_mfma_f32_16x16x32_bf16 v[74:77], v[138:141], v[196:199], v[74:77]
	v_mfma_f32_16x16x32_bf16 v[126:129], v[134:137], v[166:169], v[126:129]
	v_mfma_f32_16x16x32_bf16 v[122:125], v[142:145], v[166:169], v[122:125]
	v_mfma_f32_16x16x32_bf16 v[110:113], v[134:137], v[174:177], v[110:113]
	v_mfma_f32_16x16x32_bf16 v[106:109], v[142:145], v[174:177], v[106:109]
	v_mfma_f32_16x16x32_bf16 v[94:97], v[134:137], v[182:185], v[94:97]
	v_mfma_f32_16x16x32_bf16 v[90:93], v[142:145], v[182:185], v[90:93]
	v_mfma_f32_16x16x32_bf16 v[78:81], v[134:137], v[206:209], v[78:81]
	v_mfma_f32_16x16x32_bf16 v[74:77], v[142:145], v[206:209], v[74:77]
	s_setprio 0
	s_setprio 1
	v_mfma_f32_16x16x32_bf16 v[118:121], v[146:149], v[162:165], v[118:121]
	v_mfma_f32_16x16x32_bf16 v[114:117], v[154:157], v[162:165], v[114:117]
	v_mfma_f32_16x16x32_bf16 v[102:105], v[146:149], v[170:173], v[102:105]
	v_mfma_f32_16x16x32_bf16 v[98:101], v[154:157], v[170:173], v[98:101]
	v_mfma_f32_16x16x32_bf16 v[86:89], v[146:149], v[178:181], v[86:89]
	v_mfma_f32_16x16x32_bf16 v[82:85], v[154:157], v[178:181], v[82:85]
	v_mfma_f32_16x16x32_bf16 v[70:73], v[146:149], v[196:199], v[70:73]
	v_mfma_f32_16x16x32_bf16 v[66:69], v[154:157], v[196:199], v[66:69]
	v_mfma_f32_16x16x32_bf16 v[118:121], v[150:153], v[166:169], v[118:121]
	v_mfma_f32_16x16x32_bf16 v[114:117], v[158:161], v[166:169], v[114:117]
	v_mfma_f32_16x16x32_bf16 v[102:105], v[150:153], v[174:177], v[102:105]
	v_mfma_f32_16x16x32_bf16 v[98:101], v[158:161], v[174:177], v[98:101]
	v_mfma_f32_16x16x32_bf16 v[86:89], v[150:153], v[182:185], v[86:89]
	v_mfma_f32_16x16x32_bf16 v[82:85], v[158:161], v[182:185], v[82:85]
	v_mfma_f32_16x16x32_bf16 v[70:73], v[150:153], v[206:209], v[70:73]
	v_mfma_f32_16x16x32_bf16 v[66:69], v[158:161], v[206:209], v[66:69]
	s_barrier
	s_setprio 0
	s_add_i32 s47, s47, s33
	v_lshl_add_u64 v[210:211], s[28:29], 0, v[190:191]
	s_mov_b32 m0, s47
	ds_read_b128 v[162:165], v222 offset:16384
	ds_read_b128 v[166:169], v222 offset:17408
	ds_read_b128 v[170:173], v222 offset:18432
	ds_read_b128 v[174:177], v222 offset:19456
	ds_read_b128 v[178:181], v222 offset:20480
	ds_read_b128 v[182:185], v222 offset:21504
	ds_read_b128 v[196:199], v222 offset:22528
	ds_read_b128 v[206:209], v222 offset:23552
	global_load_lds_dwordx4 v[210:211], off
	s_add_i32 m0, s47, 0x2000
	s_add_u32 s52, s28, 0x80000
	v_lshl_add_u64 v[212:213], s[28:29], 0, v[200:201]
	s_addc_u32 s53, s29, 0
	s_add_i32 s47, s55, s33
	global_load_lds_dwordx4 v[212:213], off
	v_lshl_add_u64 v[214:215], s[52:53], 0, v[190:191]
	s_mov_b32 m0, s47
	v_lshl_add_u64 v[216:217], s[30:31], 0, v[188:189]
	global_load_lds_dwordx4 v[214:215], off
	s_add_i32 m0, s47, 0x2000
	v_lshl_add_u64 v[214:215], s[52:53], 0, v[200:201]
	global_load_lds_dwordx4 v[214:215], off
	s_mov_b32 m0, s34
	v_lshl_add_u64 v[214:215], s[30:31], 0, v[186:187]
	global_load_lds_dwordx4 v[214:215], off
	s_mov_b32 m0, s35
	s_nop 0
	global_load_lds_dwordx4 v[216:217], off
	s_waitcnt vmcnt(8) lgkmcnt(0)
	s_setprio 1
	s_barrier
	v_mfma_f32_16x16x32_bf16 v[62:65], v[130:133], v[162:165], v[62:65]
	v_mfma_f32_16x16x32_bf16 v[58:61], v[138:141], v[162:165], v[58:61]
	v_mfma_f32_16x16x32_bf16 v[46:49], v[130:133], v[170:173], v[46:49]
	v_mfma_f32_16x16x32_bf16 v[42:45], v[138:141], v[170:173], v[42:45]
	v_mfma_f32_16x16x32_bf16 v[30:33], v[130:133], v[178:181], v[30:33]
	v_mfma_f32_16x16x32_bf16 v[26:29], v[138:141], v[178:181], v[26:29]
	v_mfma_f32_16x16x32_bf16 v[14:17], v[130:133], v[196:199], v[14:17]
	v_mfma_f32_16x16x32_bf16 v[10:13], v[138:141], v[196:199], v[10:13]
	v_mfma_f32_16x16x32_bf16 v[62:65], v[134:137], v[166:169], v[62:65]
	v_mfma_f32_16x16x32_bf16 v[58:61], v[142:145], v[166:169], v[58:61]
	v_mfma_f32_16x16x32_bf16 v[46:49], v[134:137], v[174:177], v[46:49]
	v_mfma_f32_16x16x32_bf16 v[42:45], v[142:145], v[174:177], v[42:45]
	v_mfma_f32_16x16x32_bf16 v[30:33], v[134:137], v[182:185], v[30:33]
	v_mfma_f32_16x16x32_bf16 v[26:29], v[142:145], v[182:185], v[26:29]
	v_mfma_f32_16x16x32_bf16 v[14:17], v[134:137], v[206:209], v[14:17]
	v_mfma_f32_16x16x32_bf16 v[10:13], v[142:145], v[206:209], v[10:13]
	s_setprio 0
	s_setprio 1
	v_mfma_f32_16x16x32_bf16 v[54:57], v[146:149], v[162:165], v[54:57]
	v_mfma_f32_16x16x32_bf16 v[50:53], v[154:157], v[162:165], v[50:53]
	v_mfma_f32_16x16x32_bf16 v[38:41], v[146:149], v[170:173], v[38:41]
	v_mfma_f32_16x16x32_bf16 v[34:37], v[154:157], v[170:173], v[34:37]
	v_mfma_f32_16x16x32_bf16 v[22:25], v[146:149], v[178:181], v[22:25]
	v_mfma_f32_16x16x32_bf16 v[18:21], v[154:157], v[178:181], v[18:21]
	v_mfma_f32_16x16x32_bf16 v[6:9], v[146:149], v[196:199], v[6:9]
	v_mfma_f32_16x16x32_bf16 v[2:5], v[154:157], v[196:199], v[2:5]
	v_mfma_f32_16x16x32_bf16 v[54:57], v[150:153], v[166:169], v[54:57]
	v_mfma_f32_16x16x32_bf16 v[50:53], v[158:161], v[166:169], v[50:53]
	v_mfma_f32_16x16x32_bf16 v[38:41], v[150:153], v[174:177], v[38:41]
	v_mfma_f32_16x16x32_bf16 v[34:37], v[158:161], v[174:177], v[34:37]
	v_mfma_f32_16x16x32_bf16 v[22:25], v[150:153], v[182:185], v[22:25]
	v_mfma_f32_16x16x32_bf16 v[18:21], v[158:161], v[182:185], v[18:21]
	v_mfma_f32_16x16x32_bf16 v[6:9], v[150:153], v[206:209], v[6:9]
	v_mfma_f32_16x16x32_bf16 v[2:5], v[158:161], v[206:209], v[2:5]
	s_barrier
	s_setprio 0
	s_add_i32 s47, 0, 0x18000
	s_add_i32 s52, 0, 0x1c000
	v_add_u32_e32 v142, s47, v220
	v_add_u32_e32 v158, s52, v220
	ds_read_b128 v[130:133], v142
	ds_read_b128 v[134:137], v142 offset:1024
	ds_read_b128 v[138:141], v142 offset:2048
	ds_read_b128 v[142:145], v142 offset:3072
	ds_read_b128 v[146:149], v158
	ds_read_b128 v[150:153], v158 offset:1024
	ds_read_b128 v[154:157], v158 offset:2048
	ds_read_b128 v[158:161], v158 offset:3072
	s_add_u32 s30, s30, 0x80000
	s_addc_u32 s31, s31, 0
	s_mov_b32 m0, s36
	v_lshl_add_u64 v[218:219], s[30:31], 0, v[186:187]
	ds_read_b128 v[162:165], v222 offset:32768
	ds_read_b128 v[166:169], v222 offset:33792
	ds_read_b128 v[170:173], v222 offset:34816
	ds_read_b128 v[174:177], v222 offset:35840
	ds_read_b128 v[178:181], v222 offset:36864
	ds_read_b128 v[182:185], v222 offset:37888
	ds_read_b128 v[196:199], v222 offset:38912
	ds_read_b128 v[206:209], v222 offset:39936
	global_load_lds_dwordx4 v[218:219], off
	s_mov_b32 m0, s37
	v_lshl_add_u64 v[218:219], s[30:31], 0, v[188:189]
	global_load_lds_dwordx4 v[218:219], off
	s_waitcnt vmcnt(8) lgkmcnt(0)
	s_setprio 1
	s_barrier
	v_mfma_f32_16x16x32_bf16 v[126:129], v[130:133], v[162:165], v[126:129]
	v_mfma_f32_16x16x32_bf16 v[122:125], v[138:141], v[162:165], v[122:125]
	v_mfma_f32_16x16x32_bf16 v[110:113], v[130:133], v[170:173], v[110:113]
	v_mfma_f32_16x16x32_bf16 v[106:109], v[138:141], v[170:173], v[106:109]
	v_mfma_f32_16x16x32_bf16 v[94:97], v[130:133], v[178:181], v[94:97]
	v_mfma_f32_16x16x32_bf16 v[90:93], v[138:141], v[178:181], v[90:93]
	v_mfma_f32_16x16x32_bf16 v[78:81], v[130:133], v[196:199], v[78:81]
	v_mfma_f32_16x16x32_bf16 v[74:77], v[138:141], v[196:199], v[74:77]
	v_mfma_f32_16x16x32_bf16 v[126:129], v[134:137], v[166:169], v[126:129]
	v_mfma_f32_16x16x32_bf16 v[122:125], v[142:145], v[166:169], v[122:125]
	v_mfma_f32_16x16x32_bf16 v[110:113], v[134:137], v[174:177], v[110:113]
	v_mfma_f32_16x16x32_bf16 v[106:109], v[142:145], v[174:177], v[106:109]
	v_mfma_f32_16x16x32_bf16 v[94:97], v[134:137], v[182:185], v[94:97]
	v_mfma_f32_16x16x32_bf16 v[90:93], v[142:145], v[182:185], v[90:93]
	v_mfma_f32_16x16x32_bf16 v[78:81], v[134:137], v[206:209], v[78:81]
	v_mfma_f32_16x16x32_bf16 v[74:77], v[142:145], v[206:209], v[74:77]
	s_setprio 0
	s_setprio 1
	v_mfma_f32_16x16x32_bf16 v[118:121], v[146:149], v[162:165], v[118:121]
	v_mfma_f32_16x16x32_bf16 v[114:117], v[154:157], v[162:165], v[114:117]
	v_mfma_f32_16x16x32_bf16 v[102:105], v[146:149], v[170:173], v[102:105]
	v_mfma_f32_16x16x32_bf16 v[98:101], v[154:157], v[170:173], v[98:101]
	v_mfma_f32_16x16x32_bf16 v[86:89], v[146:149], v[178:181], v[86:89]
	v_mfma_f32_16x16x32_bf16 v[82:85], v[154:157], v[178:181], v[82:85]
	v_mfma_f32_16x16x32_bf16 v[70:73], v[146:149], v[196:199], v[70:73]
	v_mfma_f32_16x16x32_bf16 v[66:69], v[154:157], v[196:199], v[66:69]
	v_mfma_f32_16x16x32_bf16 v[118:121], v[150:153], v[166:169], v[118:121]
	v_mfma_f32_16x16x32_bf16 v[114:117], v[158:161], v[166:169], v[114:117]
	v_mfma_f32_16x16x32_bf16 v[102:105], v[150:153], v[174:177], v[102:105]
	v_mfma_f32_16x16x32_bf16 v[98:101], v[158:161], v[174:177], v[98:101]
	v_mfma_f32_16x16x32_bf16 v[86:89], v[150:153], v[182:185], v[86:89]
	v_mfma_f32_16x16x32_bf16 v[82:85], v[158:161], v[182:185], v[82:85]
	v_mfma_f32_16x16x32_bf16 v[70:73], v[150:153], v[206:209], v[70:73]
	v_mfma_f32_16x16x32_bf16 v[66:69], v[158:161], v[206:209], v[66:69]
	s_barrier
	s_setprio 0
	s_add_i32 s30, s47, s33
	v_lshl_add_u64 v[210:211], v[210:211], 0, s[58:59]
	s_mov_b32 m0, s30
	ds_read_b128 v[162:165], v222 offset:49152
	ds_read_b128 v[166:169], v222 offset:50176
	ds_read_b128 v[170:173], v222 offset:51200
	ds_read_b128 v[174:177], v222 offset:52224
	ds_read_b128 v[178:181], v222 offset:53248
	ds_read_b128 v[182:185], v222 offset:54272
	ds_read_b128 v[196:199], v222 offset:55296
	ds_read_b128 v[206:209], v222 offset:56320
	global_load_lds_dwordx4 v[210:211], off
	s_add_i32 m0, s30, 0x2000
	s_add_u32 s28, s28, 0x80080
	v_lshl_add_u64 v[210:211], v[212:213], 0, s[58:59]
	s_addc_u32 s29, s29, 0
	s_add_i32 s30, s52, s33
	global_load_lds_dwordx4 v[210:211], off
	s_mov_b32 m0, s30
	v_lshl_add_u64 v[210:211], s[28:29], 0, v[190:191]
	global_load_lds_dwordx4 v[210:211], off
	s_add_i32 m0, s30, 0x2000
	v_lshl_add_u64 v[210:211], s[28:29], 0, v[200:201]
	global_load_lds_dwordx4 v[210:211], off
	s_mov_b32 m0, s38
	v_lshl_add_u64 v[210:211], v[214:215], 0, s[58:59]
	global_load_lds_dwordx4 v[210:211], off
	s_mov_b32 m0, s39
	v_lshl_add_u64 v[210:211], v[216:217], 0, s[58:59]
	global_load_lds_dwordx4 v[210:211], off
	s_waitcnt vmcnt(8) lgkmcnt(0)
	s_setprio 1
	s_barrier
	v_mfma_f32_16x16x32_bf16 v[62:65], v[130:133], v[162:165], v[62:65]
	v_mfma_f32_16x16x32_bf16 v[58:61], v[138:141], v[162:165], v[58:61]
	v_mfma_f32_16x16x32_bf16 v[46:49], v[130:133], v[170:173], v[46:49]
	v_mfma_f32_16x16x32_bf16 v[42:45], v[138:141], v[170:173], v[42:45]
	v_mfma_f32_16x16x32_bf16 v[30:33], v[130:133], v[178:181], v[30:33]
	v_mfma_f32_16x16x32_bf16 v[26:29], v[138:141], v[178:181], v[26:29]
	v_mfma_f32_16x16x32_bf16 v[14:17], v[130:133], v[196:199], v[14:17]
	v_mfma_f32_16x16x32_bf16 v[10:13], v[138:141], v[196:199], v[10:13]
	v_mfma_f32_16x16x32_bf16 v[62:65], v[134:137], v[166:169], v[62:65]
	v_mfma_f32_16x16x32_bf16 v[58:61], v[142:145], v[166:169], v[58:61]
	v_mfma_f32_16x16x32_bf16 v[46:49], v[134:137], v[174:177], v[46:49]
	v_mfma_f32_16x16x32_bf16 v[42:45], v[142:145], v[174:177], v[42:45]
	v_mfma_f32_16x16x32_bf16 v[30:33], v[134:137], v[182:185], v[30:33]
	v_mfma_f32_16x16x32_bf16 v[26:29], v[142:145], v[182:185], v[26:29]
	v_mfma_f32_16x16x32_bf16 v[14:17], v[134:137], v[206:209], v[14:17]
	v_mfma_f32_16x16x32_bf16 v[10:13], v[142:145], v[206:209], v[10:13]
	s_setprio 0
	s_setprio 1
	v_mfma_f32_16x16x32_bf16 v[54:57], v[146:149], v[162:165], v[54:57]
	v_mfma_f32_16x16x32_bf16 v[50:53], v[154:157], v[162:165], v[50:53]
	v_mfma_f32_16x16x32_bf16 v[38:41], v[146:149], v[170:173], v[38:41]
	v_mfma_f32_16x16x32_bf16 v[34:37], v[154:157], v[170:173], v[34:37]
	v_mfma_f32_16x16x32_bf16 v[22:25], v[146:149], v[178:181], v[22:25]
	v_mfma_f32_16x16x32_bf16 v[18:21], v[154:157], v[178:181], v[18:21]
	v_mfma_f32_16x16x32_bf16 v[6:9], v[146:149], v[196:199], v[6:9]
	v_mfma_f32_16x16x32_bf16 v[2:5], v[154:157], v[196:199], v[2:5]
	v_mfma_f32_16x16x32_bf16 v[54:57], v[150:153], v[166:169], v[54:57]
	v_mfma_f32_16x16x32_bf16 v[50:53], v[158:161], v[166:169], v[50:53]
	v_mfma_f32_16x16x32_bf16 v[38:41], v[150:153], v[174:177], v[38:41]
	v_mfma_f32_16x16x32_bf16 v[34:37], v[158:161], v[174:177], v[34:37]
	v_mfma_f32_16x16x32_bf16 v[22:25], v[150:153], v[182:185], v[22:25]
	v_mfma_f32_16x16x32_bf16 v[18:21], v[158:161], v[182:185], v[18:21]
	v_mfma_f32_16x16x32_bf16 v[6:9], v[150:153], v[206:209], v[6:9]
	v_mfma_f32_16x16x32_bf16 v[2:5], v[158:161], v[206:209], v[2:5]
	s_barrier
	s_setprio 0
	s_add_i32 s46, s46, 2
	s_add_u32 s26, s26, 0x100
	s_addc_u32 s27, s27, 0
	s_add_u32 s42, s42, 0x100
	s_addc_u32 s43, s43, 0
	s_cmp_gt_u32 s46, 29
	s_cbranch_scc0 .LBB0_772

.LBB0_800:
	s_add_u32 s26, s24, 0xfff80080
	s_addc_u32 s27, s25, -1
	s_add_i32 s56, 0, 0x10000
	s_cmp_eq_u32 s55, 28
	s_cselect_b32 s29, s11, s27
	s_cselect_b32 s28, s21, s26
	s_cselect_b32 s27, s9, s53
	s_cselect_b32 s26, s47, s52
	s_add_i32 s60, 0, 0x14000
	v_add_u32_e32 v142, s56, v238
	v_add_u32_e32 v158, s60, v238
	ds_read_b128 v[130:133], v142
	ds_read_b128 v[134:137], v142 offset:1024
	ds_read_b128 v[138:141], v142 offset:2048
	ds_read_b128 v[142:145], v142 offset:3072
	ds_read_b128 v[146:149], v158
	ds_read_b128 v[150:153], v158 offset:1024
	ds_read_b128 v[154:157], v158 offset:2048
	ds_read_b128 v[158:161], v158 offset:3072
	v_lshl_add_u64 v[210:211], s[24:25], 0, v[206:207]
	s_add_i32 m0, s23, 0xc000
	ds_read_b128 v[162:165], v240
	ds_read_b128 v[166:169], v240 offset:1024
	ds_read_b128 v[170:173], v240 offset:2048
	ds_read_b128 v[174:177], v240 offset:3072
	ds_read_b128 v[178:181], v240 offset:4096
	ds_read_b128 v[182:185], v240 offset:5120
	ds_read_b128 v[186:189], v240 offset:6144
	ds_read_b128 v[196:199], v240 offset:7168
	global_load_lds_dwordx4 v[210:211], off
	s_add_i32 m0, s23, 0xe000
	v_lshl_add_u64 v[210:211], s[24:25], 0, v[208:209]
	global_load_lds_dwordx4 v[210:211], off
	s_waitcnt vmcnt(8) lgkmcnt(0)
	s_setprio 1
	s_barrier
	v_mfma_f32_16x16x32_bf16 v[126:129], v[130:133], v[162:165], v[126:129]
	v_mfma_f32_16x16x32_bf16 v[122:125], v[138:141], v[162:165], v[122:125]
	v_mfma_f32_16x16x32_bf16 v[110:113], v[130:133], v[170:173], v[110:113]
	v_mfma_f32_16x16x32_bf16 v[106:109], v[138:141], v[170:173], v[106:109]
	v_mfma_f32_16x16x32_bf16 v[98:101], v[130:133], v[178:181], v[98:101]
	v_mfma_f32_16x16x32_bf16 v[90:93], v[138:141], v[178:181], v[90:93]
	v_mfma_f32_16x16x32_bf16 v[82:85], v[130:133], v[186:189], v[82:85]
	v_mfma_f32_16x16x32_bf16 v[74:77], v[138:141], v[186:189], v[74:77]
	v_mfma_f32_16x16x32_bf16 v[126:129], v[134:137], v[166:169], v[126:129]
	v_mfma_f32_16x16x32_bf16 v[122:125], v[142:145], v[166:169], v[122:125]
	v_mfma_f32_16x16x32_bf16 v[110:113], v[134:137], v[174:177], v[110:113]
	v_mfma_f32_16x16x32_bf16 v[106:109], v[142:145], v[174:177], v[106:109]
	v_mfma_f32_16x16x32_bf16 v[98:101], v[134:137], v[182:185], v[98:101]
	v_mfma_f32_16x16x32_bf16 v[90:93], v[142:145], v[182:185], v[90:93]
	v_mfma_f32_16x16x32_bf16 v[82:85], v[134:137], v[196:199], v[82:85]
	v_mfma_f32_16x16x32_bf16 v[74:77], v[142:145], v[196:199], v[74:77]
	s_setprio 0
	s_setprio 1
	v_mfma_f32_16x16x32_bf16 v[118:121], v[146:149], v[162:165], v[118:121]
	v_mfma_f32_16x16x32_bf16 v[114:117], v[154:157], v[162:165], v[114:117]
	v_mfma_f32_16x16x32_bf16 v[102:105], v[146:149], v[170:173], v[102:105]
	v_mfma_f32_16x16x32_bf16 v[94:97], v[154:157], v[170:173], v[94:97]
	v_mfma_f32_16x16x32_bf16 v[86:89], v[146:149], v[178:181], v[86:89]
	v_mfma_f32_16x16x32_bf16 v[78:81], v[154:157], v[178:181], v[78:81]
	v_mfma_f32_16x16x32_bf16 v[70:73], v[146:149], v[186:189], v[70:73]
	v_mfma_f32_16x16x32_bf16 v[66:69], v[154:157], v[186:189], v[66:69]
	v_mfma_f32_16x16x32_bf16 v[118:121], v[150:153], v[166:169], v[118:121]
	v_mfma_f32_16x16x32_bf16 v[114:117], v[158:161], v[166:169], v[114:117]
	v_mfma_f32_16x16x32_bf16 v[102:105], v[150:153], v[174:177], v[102:105]
	v_mfma_f32_16x16x32_bf16 v[94:97], v[158:161], v[174:177], v[94:97]
	v_mfma_f32_16x16x32_bf16 v[86:89], v[150:153], v[182:185], v[86:89]
	v_mfma_f32_16x16x32_bf16 v[78:81], v[158:161], v[182:185], v[78:81]
	v_mfma_f32_16x16x32_bf16 v[70:73], v[150:153], v[196:199], v[70:73]
	v_mfma_f32_16x16x32_bf16 v[66:69], v[158:161], v[196:199], v[66:69]
	s_barrier
	s_setprio 0
	s_add_i32 s56, s56, s34
	v_lshl_add_u64 v[210:211], s[26:27], 0, v[190:191]
	s_mov_b32 m0, s56
	ds_read_b128 v[162:165], v240 offset:16384
	ds_read_b128 v[166:169], v240 offset:17408
	ds_read_b128 v[170:173], v240 offset:18432
	ds_read_b128 v[174:177], v240 offset:19456
	ds_read_b128 v[178:181], v240 offset:20480
	ds_read_b128 v[182:185], v240 offset:21504
	ds_read_b128 v[186:189], v240 offset:22528
	ds_read_b128 v[196:199], v240 offset:23552
	global_load_lds_dwordx4 v[210:211], off
	s_add_i32 m0, s56, 0x2000
	s_add_u32 s56, s26, 0x80000
	v_lshl_add_u64 v[212:213], s[26:27], 0, v[204:205]
	s_addc_u32 s57, s27, 0
	s_add_i32 s60, s60, s34
	global_load_lds_dwordx4 v[212:213], off
	v_lshl_add_u64 v[214:215], s[56:57], 0, v[190:191]
	s_mov_b32 m0, s60
	v_lshl_add_u64 v[216:217], s[28:29], 0, v[202:203]
	global_load_lds_dwordx4 v[214:215], off
	s_add_i32 m0, s60, 0x2000
	v_lshl_add_u64 v[214:215], s[56:57], 0, v[204:205]
	global_load_lds_dwordx4 v[214:215], off
	s_mov_b32 m0, s23
	v_lshl_add_u64 v[214:215], s[28:29], 0, v[200:201]
	global_load_lds_dwordx4 v[214:215], off
	s_mov_b32 m0, s35
	s_nop 0
	global_load_lds_dwordx4 v[216:217], off
	s_waitcnt vmcnt(8) lgkmcnt(0)
	s_setprio 1
	s_barrier
	v_mfma_f32_16x16x32_bf16 v[62:65], v[130:133], v[162:165], v[62:65]
	v_mfma_f32_16x16x32_bf16 v[58:61], v[138:141], v[162:165], v[58:61]
	v_mfma_f32_16x16x32_bf16 v[50:53], v[130:133], v[170:173], v[50:53]
	v_mfma_f32_16x16x32_bf16 v[42:45], v[138:141], v[170:173], v[42:45]
	v_mfma_f32_16x16x32_bf16 v[34:37], v[130:133], v[178:181], v[34:37]
	v_mfma_f32_16x16x32_bf16 v[26:29], v[138:141], v[178:181], v[26:29]
	v_mfma_f32_16x16x32_bf16 v[18:21], v[130:133], v[186:189], v[18:21]
	v_mfma_f32_16x16x32_bf16 v[10:13], v[138:141], v[186:189], v[10:13]
	v_mfma_f32_16x16x32_bf16 v[62:65], v[134:137], v[166:169], v[62:65]
	v_mfma_f32_16x16x32_bf16 v[58:61], v[142:145], v[166:169], v[58:61]
	v_mfma_f32_16x16x32_bf16 v[50:53], v[134:137], v[174:177], v[50:53]
	v_mfma_f32_16x16x32_bf16 v[42:45], v[142:145], v[174:177], v[42:45]
	v_mfma_f32_16x16x32_bf16 v[34:37], v[134:137], v[182:185], v[34:37]
	v_mfma_f32_16x16x32_bf16 v[26:29], v[142:145], v[182:185], v[26:29]
	v_mfma_f32_16x16x32_bf16 v[18:21], v[134:137], v[196:199], v[18:21]
	v_mfma_f32_16x16x32_bf16 v[10:13], v[142:145], v[196:199], v[10:13]
	s_setprio 0
	s_setprio 1
	v_mfma_f32_16x16x32_bf16 v[54:57], v[146:149], v[162:165], v[54:57]
	v_mfma_f32_16x16x32_bf16 v[46:49], v[154:157], v[162:165], v[46:49]
	v_mfma_f32_16x16x32_bf16 v[38:41], v[146:149], v[170:173], v[38:41]
	v_mfma_f32_16x16x32_bf16 v[30:33], v[154:157], v[170:173], v[30:33]
	v_mfma_f32_16x16x32_bf16 v[22:25], v[146:149], v[178:181], v[22:25]
	v_mfma_f32_16x16x32_bf16 v[14:17], v[154:157], v[178:181], v[14:17]
	v_mfma_f32_16x16x32_bf16 v[6:9], v[146:149], v[186:189], v[6:9]
	v_mfma_f32_16x16x32_bf16 v[2:5], v[154:157], v[186:189], v[2:5]
	v_mfma_f32_16x16x32_bf16 v[54:57], v[150:153], v[166:169], v[54:57]
	v_mfma_f32_16x16x32_bf16 v[46:49], v[158:161], v[166:169], v[46:49]
	v_mfma_f32_16x16x32_bf16 v[38:41], v[150:153], v[174:177], v[38:41]
	v_mfma_f32_16x16x32_bf16 v[30:33], v[158:161], v[174:177], v[30:33]
	v_mfma_f32_16x16x32_bf16 v[22:25], v[150:153], v[182:185], v[22:25]
	v_mfma_f32_16x16x32_bf16 v[14:17], v[158:161], v[182:185], v[14:17]
	v_mfma_f32_16x16x32_bf16 v[6:9], v[150:153], v[196:199], v[6:9]
	v_mfma_f32_16x16x32_bf16 v[2:5], v[158:161], v[196:199], v[2:5]
	s_barrier
	s_setprio 0
	s_add_i32 s56, 0, 0x18000
	s_add_i32 s57, 0, 0x1c000
	v_add_u32_e32 v142, s56, v238
	v_add_u32_e32 v158, s57, v238
	ds_read_b128 v[130:133], v142
	ds_read_b128 v[134:137], v142 offset:1024
	ds_read_b128 v[138:141], v142 offset:2048
	ds_read_b128 v[142:145], v142 offset:3072
	ds_read_b128 v[146:149], v158
	ds_read_b128 v[150:153], v158 offset:1024
	ds_read_b128 v[154:157], v158 offset:2048
	ds_read_b128 v[158:161], v158 offset:3072
	s_add_u32 s28, s28, 0x80000
	s_addc_u32 s29, s29, 0
	s_mov_b32 m0, s41
	v_lshl_add_u64 v[218:219], s[28:29], 0, v[200:201]
	ds_read_b128 v[162:165], v240 offset:32768
	ds_read_b128 v[166:169], v240 offset:33792
	ds_read_b128 v[170:173], v240 offset:34816
	ds_read_b128 v[174:177], v240 offset:35840
	ds_read_b128 v[178:181], v240 offset:36864
	ds_read_b128 v[182:185], v240 offset:37888
	ds_read_b128 v[186:189], v240 offset:38912
	ds_read_b128 v[196:199], v240 offset:39936
	global_load_lds_dwordx4 v[218:219], off
	s_mov_b32 m0, s42
	v_lshl_add_u64 v[218:219], s[28:29], 0, v[202:203]
	global_load_lds_dwordx4 v[218:219], off
	s_waitcnt vmcnt(8) lgkmcnt(0)
	s_setprio 1
	s_barrier
	v_mfma_f32_16x16x32_bf16 v[126:129], v[130:133], v[162:165], v[126:129]
	v_mfma_f32_16x16x32_bf16 v[122:125], v[138:141], v[162:165], v[122:125]
	v_mfma_f32_16x16x32_bf16 v[110:113], v[130:133], v[170:173], v[110:113]
	v_mfma_f32_16x16x32_bf16 v[106:109], v[138:141], v[170:173], v[106:109]
	v_mfma_f32_16x16x32_bf16 v[98:101], v[130:133], v[178:181], v[98:101]
	v_mfma_f32_16x16x32_bf16 v[90:93], v[138:141], v[178:181], v[90:93]
	v_mfma_f32_16x16x32_bf16 v[82:85], v[130:133], v[186:189], v[82:85]
	v_mfma_f32_16x16x32_bf16 v[74:77], v[138:141], v[186:189], v[74:77]
	v_mfma_f32_16x16x32_bf16 v[126:129], v[134:137], v[166:169], v[126:129]
	v_mfma_f32_16x16x32_bf16 v[122:125], v[142:145], v[166:169], v[122:125]
	v_mfma_f32_16x16x32_bf16 v[110:113], v[134:137], v[174:177], v[110:113]
	v_mfma_f32_16x16x32_bf16 v[106:109], v[142:145], v[174:177], v[106:109]
	v_mfma_f32_16x16x32_bf16 v[98:101], v[134:137], v[182:185], v[98:101]
	v_mfma_f32_16x16x32_bf16 v[90:93], v[142:145], v[182:185], v[90:93]
	v_mfma_f32_16x16x32_bf16 v[82:85], v[134:137], v[196:199], v[82:85]
	v_mfma_f32_16x16x32_bf16 v[74:77], v[142:145], v[196:199], v[74:77]
	s_setprio 0
	s_setprio 1
	v_mfma_f32_16x16x32_bf16 v[118:121], v[146:149], v[162:165], v[118:121]
	v_mfma_f32_16x16x32_bf16 v[114:117], v[154:157], v[162:165], v[114:117]
	v_mfma_f32_16x16x32_bf16 v[102:105], v[146:149], v[170:173], v[102:105]
	v_mfma_f32_16x16x32_bf16 v[94:97], v[154:157], v[170:173], v[94:97]
	v_mfma_f32_16x16x32_bf16 v[86:89], v[146:149], v[178:181], v[86:89]
	v_mfma_f32_16x16x32_bf16 v[78:81], v[154:157], v[178:181], v[78:81]
	v_mfma_f32_16x16x32_bf16 v[70:73], v[146:149], v[186:189], v[70:73]
	v_mfma_f32_16x16x32_bf16 v[66:69], v[154:157], v[186:189], v[66:69]
	v_mfma_f32_16x16x32_bf16 v[118:121], v[150:153], v[166:169], v[118:121]
	v_mfma_f32_16x16x32_bf16 v[114:117], v[158:161], v[166:169], v[114:117]
	v_mfma_f32_16x16x32_bf16 v[102:105], v[150:153], v[174:177], v[102:105]
	v_mfma_f32_16x16x32_bf16 v[94:97], v[158:161], v[174:177], v[94:97]
	v_mfma_f32_16x16x32_bf16 v[86:89], v[150:153], v[182:185], v[86:89]
	v_mfma_f32_16x16x32_bf16 v[78:81], v[158:161], v[182:185], v[78:81]
	v_mfma_f32_16x16x32_bf16 v[70:73], v[150:153], v[196:199], v[70:73]
	v_mfma_f32_16x16x32_bf16 v[66:69], v[158:161], v[196:199], v[66:69]
	s_barrier
	s_setprio 0
	s_add_i32 s28, s56, s34
	v_lshl_add_u64 v[210:211], v[210:211], 0, s[58:59]
	s_mov_b32 m0, s28
	ds_read_b128 v[162:165], v240 offset:49152
	ds_read_b128 v[166:169], v240 offset:50176
	ds_read_b128 v[170:173], v240 offset:51200
	ds_read_b128 v[174:177], v240 offset:52224
	ds_read_b128 v[178:181], v240 offset:53248
	ds_read_b128 v[182:185], v240 offset:54272
	ds_read_b128 v[186:189], v240 offset:55296
	ds_read_b128 v[196:199], v240 offset:56320
	global_load_lds_dwordx4 v[210:211], off
	s_add_i32 m0, s28, 0x2000
	s_add_u32 s26, s26, 0x80080
	v_lshl_add_u64 v[210:211], v[212:213], 0, s[58:59]
	s_addc_u32 s27, s27, 0
	s_add_i32 s28, s57, s34
	global_load_lds_dwordx4 v[210:211], off
	s_mov_b32 m0, s28
	v_lshl_add_u64 v[210:211], s[26:27], 0, v[190:191]
	global_load_lds_dwordx4 v[210:211], off
	s_add_i32 m0, s28, 0x2000
	v_lshl_add_u64 v[210:211], s[26:27], 0, v[204:205]
	global_load_lds_dwordx4 v[210:211], off
	s_mov_b32 m0, s43
	v_lshl_add_u64 v[210:211], v[214:215], 0, s[58:59]
	global_load_lds_dwordx4 v[210:211], off
	s_mov_b32 m0, s46
	v_lshl_add_u64 v[210:211], v[216:217], 0, s[58:59]
	global_load_lds_dwordx4 v[210:211], off
	s_waitcnt vmcnt(8) lgkmcnt(0)
	s_setprio 1
	s_barrier
	v_mfma_f32_16x16x32_bf16 v[62:65], v[130:133], v[162:165], v[62:65]
	v_mfma_f32_16x16x32_bf16 v[58:61], v[138:141], v[162:165], v[58:61]
	v_mfma_f32_16x16x32_bf16 v[50:53], v[130:133], v[170:173], v[50:53]
	v_mfma_f32_16x16x32_bf16 v[42:45], v[138:141], v[170:173], v[42:45]
	v_mfma_f32_16x16x32_bf16 v[34:37], v[130:133], v[178:181], v[34:37]
	v_mfma_f32_16x16x32_bf16 v[26:29], v[138:141], v[178:181], v[26:29]
	v_mfma_f32_16x16x32_bf16 v[18:21], v[130:133], v[186:189], v[18:21]
	v_mfma_f32_16x16x32_bf16 v[10:13], v[138:141], v[186:189], v[10:13]
	v_mfma_f32_16x16x32_bf16 v[62:65], v[134:137], v[166:169], v[62:65]
	v_mfma_f32_16x16x32_bf16 v[58:61], v[142:145], v[166:169], v[58:61]
	v_mfma_f32_16x16x32_bf16 v[50:53], v[134:137], v[174:177], v[50:53]
	v_mfma_f32_16x16x32_bf16 v[42:45], v[142:145], v[174:177], v[42:45]
	v_mfma_f32_16x16x32_bf16 v[34:37], v[134:137], v[182:185], v[34:37]
	v_mfma_f32_16x16x32_bf16 v[26:29], v[142:145], v[182:185], v[26:29]
	v_mfma_f32_16x16x32_bf16 v[18:21], v[134:137], v[196:199], v[18:21]
	v_mfma_f32_16x16x32_bf16 v[10:13], v[142:145], v[196:199], v[10:13]
	s_setprio 0
	s_setprio 1
	v_mfma_f32_16x16x32_bf16 v[54:57], v[146:149], v[162:165], v[54:57]
	v_mfma_f32_16x16x32_bf16 v[46:49], v[154:157], v[162:165], v[46:49]
	v_mfma_f32_16x16x32_bf16 v[38:41], v[146:149], v[170:173], v[38:41]
	v_mfma_f32_16x16x32_bf16 v[30:33], v[154:157], v[170:173], v[30:33]
	v_mfma_f32_16x16x32_bf16 v[22:25], v[146:149], v[178:181], v[22:25]
	v_mfma_f32_16x16x32_bf16 v[14:17], v[154:157], v[178:181], v[14:17]
	v_mfma_f32_16x16x32_bf16 v[6:9], v[146:149], v[186:189], v[6:9]
	v_mfma_f32_16x16x32_bf16 v[2:5], v[154:157], v[186:189], v[2:5]
	v_mfma_f32_16x16x32_bf16 v[54:57], v[150:153], v[166:169], v[54:57]
	v_mfma_f32_16x16x32_bf16 v[46:49], v[158:161], v[166:169], v[46:49]
	v_mfma_f32_16x16x32_bf16 v[38:41], v[150:153], v[174:177], v[38:41]
	v_mfma_f32_16x16x32_bf16 v[30:33], v[158:161], v[174:177], v[30:33]
	v_mfma_f32_16x16x32_bf16 v[22:25], v[150:153], v[182:185], v[22:25]
	v_mfma_f32_16x16x32_bf16 v[14:17], v[158:161], v[182:185], v[14:17]
	v_mfma_f32_16x16x32_bf16 v[6:9], v[150:153], v[196:199], v[6:9]
	v_mfma_f32_16x16x32_bf16 v[2:5], v[158:161], v[196:199], v[2:5]
	s_barrier
	s_setprio 0
	s_add_i32 s55, s55, 2
	s_add_u32 s24, s24, 0x100
	s_addc_u32 s25, s25, 0
	s_add_u32 s52, s52, 0x100
	s_addc_u32 s53, s53, 0
	s_cmp_gt_u32 s55, 29
	s_cbranch_scc0 .LBB0_800

.LBB0_823:
	s_add_u32 s34, s30, 0xfff80080
	s_addc_u32 s35, s31, -1
	s_add_i32 s90, 0, 0x10000
	s_cmp_eq_u32 s89, 28
	s_cselect_b32 s53, s17, s35
	s_cselect_b32 s52, s27, s34
	s_cselect_b32 s35, s15, s88
	s_cselect_b32 s34, s29, s81
	s_add_i32 s96, 0, 0x14000
	v_add_u32_e32 v142, s90, v220
	v_add_u32_e32 v158, s96, v220
	ds_read_b128 v[130:133], v142
	ds_read_b128 v[134:137], v142 offset:1024
	ds_read_b128 v[138:141], v142 offset:2048
	ds_read_b128 v[142:145], v142 offset:3072
	ds_read_b128 v[146:149], v158
	ds_read_b128 v[150:153], v158 offset:1024
	ds_read_b128 v[154:157], v158 offset:2048
	ds_read_b128 v[158:161], v158 offset:3072
	v_lshl_add_u64 v[210:211], s[30:31], 0, v[202:203]
	s_add_i32 m0, s55, 0xc000
	ds_read_b128 v[162:165], v222
	ds_read_b128 v[166:169], v222 offset:1024
	ds_read_b128 v[170:173], v222 offset:2048
	ds_read_b128 v[174:177], v222 offset:3072
	ds_read_b128 v[178:181], v222 offset:4096
	ds_read_b128 v[182:185], v222 offset:5120
	ds_read_b128 v[196:199], v222 offset:6144
	ds_read_b128 v[206:209], v222 offset:7168
	global_load_lds_dwordx4 v[210:211], off
	s_add_i32 m0, s55, 0xe000
	v_lshl_add_u64 v[210:211], s[30:31], 0, v[204:205]
	global_load_lds_dwordx4 v[210:211], off
	s_waitcnt vmcnt(8) lgkmcnt(0)
	s_setprio 1
	s_barrier
	v_mfma_f32_16x16x32_bf16 v[126:129], v[130:133], v[162:165], v[126:129]
	v_mfma_f32_16x16x32_bf16 v[122:125], v[138:141], v[162:165], v[122:125]
	v_mfma_f32_16x16x32_bf16 v[110:113], v[130:133], v[170:173], v[110:113]
	v_mfma_f32_16x16x32_bf16 v[106:109], v[138:141], v[170:173], v[106:109]
	v_mfma_f32_16x16x32_bf16 v[94:97], v[130:133], v[178:181], v[94:97]
	v_mfma_f32_16x16x32_bf16 v[90:93], v[138:141], v[178:181], v[90:93]
	v_mfma_f32_16x16x32_bf16 v[78:81], v[130:133], v[196:199], v[78:81]
	v_mfma_f32_16x16x32_bf16 v[74:77], v[138:141], v[196:199], v[74:77]
	v_mfma_f32_16x16x32_bf16 v[126:129], v[134:137], v[166:169], v[126:129]
	v_mfma_f32_16x16x32_bf16 v[122:125], v[142:145], v[166:169], v[122:125]
	v_mfma_f32_16x16x32_bf16 v[110:113], v[134:137], v[174:177], v[110:113]
	v_mfma_f32_16x16x32_bf16 v[106:109], v[142:145], v[174:177], v[106:109]
	v_mfma_f32_16x16x32_bf16 v[94:97], v[134:137], v[182:185], v[94:97]
	v_mfma_f32_16x16x32_bf16 v[90:93], v[142:145], v[182:185], v[90:93]
	v_mfma_f32_16x16x32_bf16 v[78:81], v[134:137], v[206:209], v[78:81]
	v_mfma_f32_16x16x32_bf16 v[74:77], v[142:145], v[206:209], v[74:77]
	s_setprio 0
	s_setprio 1
	v_mfma_f32_16x16x32_bf16 v[118:121], v[146:149], v[162:165], v[118:121]
	v_mfma_f32_16x16x32_bf16 v[114:117], v[154:157], v[162:165], v[114:117]
	v_mfma_f32_16x16x32_bf16 v[102:105], v[146:149], v[170:173], v[102:105]
	v_mfma_f32_16x16x32_bf16 v[98:101], v[154:157], v[170:173], v[98:101]
	v_mfma_f32_16x16x32_bf16 v[86:89], v[146:149], v[178:181], v[86:89]
	v_mfma_f32_16x16x32_bf16 v[82:85], v[154:157], v[178:181], v[82:85]
	v_mfma_f32_16x16x32_bf16 v[70:73], v[146:149], v[196:199], v[70:73]
	v_mfma_f32_16x16x32_bf16 v[66:69], v[154:157], v[196:199], v[66:69]
	v_mfma_f32_16x16x32_bf16 v[118:121], v[150:153], v[166:169], v[118:121]
	v_mfma_f32_16x16x32_bf16 v[114:117], v[158:161], v[166:169], v[114:117]
	v_mfma_f32_16x16x32_bf16 v[102:105], v[150:153], v[174:177], v[102:105]
	v_mfma_f32_16x16x32_bf16 v[98:101], v[158:161], v[174:177], v[98:101]
	v_mfma_f32_16x16x32_bf16 v[86:89], v[150:153], v[182:185], v[86:89]
	v_mfma_f32_16x16x32_bf16 v[82:85], v[158:161], v[182:185], v[82:85]
	v_mfma_f32_16x16x32_bf16 v[70:73], v[150:153], v[206:209], v[70:73]
	v_mfma_f32_16x16x32_bf16 v[66:69], v[158:161], v[206:209], v[66:69]
	s_barrier
	s_setprio 0
	s_add_i32 s90, s90, s47
	v_lshl_add_u64 v[210:211], s[34:35], 0, v[190:191]
	s_mov_b32 m0, s90
	ds_read_b128 v[162:165], v222 offset:16384
	ds_read_b128 v[166:169], v222 offset:17408
	ds_read_b128 v[170:173], v222 offset:18432
	ds_read_b128 v[174:177], v222 offset:19456
	ds_read_b128 v[178:181], v222 offset:20480
	ds_read_b128 v[182:185], v222 offset:21504
	ds_read_b128 v[196:199], v222 offset:22528
	ds_read_b128 v[206:209], v222 offset:23552
	global_load_lds_dwordx4 v[210:211], off
	s_add_i32 m0, s90, 0x2000
	s_add_u32 s90, s34, 0x80000
	v_lshl_add_u64 v[212:213], s[34:35], 0, v[200:201]
	s_addc_u32 s91, s35, 0
	s_add_i32 s96, s96, s47
	global_load_lds_dwordx4 v[212:213], off
	v_lshl_add_u64 v[214:215], s[90:91], 0, v[190:191]
	s_mov_b32 m0, s96
	v_lshl_add_u64 v[216:217], s[52:53], 0, v[188:189]
	global_load_lds_dwordx4 v[214:215], off
	s_add_i32 m0, s96, 0x2000
	v_lshl_add_u64 v[214:215], s[90:91], 0, v[200:201]
	global_load_lds_dwordx4 v[214:215], off
	s_mov_b32 m0, s55
	v_lshl_add_u64 v[214:215], s[52:53], 0, v[186:187]
	global_load_lds_dwordx4 v[214:215], off
	s_mov_b32 m0, s56
	s_nop 0
	global_load_lds_dwordx4 v[216:217], off
	s_waitcnt vmcnt(8) lgkmcnt(0)
	s_setprio 1
	s_barrier
	v_mfma_f32_16x16x32_bf16 v[62:65], v[130:133], v[162:165], v[62:65]
	v_mfma_f32_16x16x32_bf16 v[58:61], v[138:141], v[162:165], v[58:61]
	v_mfma_f32_16x16x32_bf16 v[46:49], v[130:133], v[170:173], v[46:49]
	v_mfma_f32_16x16x32_bf16 v[42:45], v[138:141], v[170:173], v[42:45]
	v_mfma_f32_16x16x32_bf16 v[30:33], v[130:133], v[178:181], v[30:33]
	v_mfma_f32_16x16x32_bf16 v[26:29], v[138:141], v[178:181], v[26:29]
	v_mfma_f32_16x16x32_bf16 v[14:17], v[130:133], v[196:199], v[14:17]
	v_mfma_f32_16x16x32_bf16 v[10:13], v[138:141], v[196:199], v[10:13]
	v_mfma_f32_16x16x32_bf16 v[62:65], v[134:137], v[166:169], v[62:65]
	v_mfma_f32_16x16x32_bf16 v[58:61], v[142:145], v[166:169], v[58:61]
	v_mfma_f32_16x16x32_bf16 v[46:49], v[134:137], v[174:177], v[46:49]
	v_mfma_f32_16x16x32_bf16 v[42:45], v[142:145], v[174:177], v[42:45]
	v_mfma_f32_16x16x32_bf16 v[30:33], v[134:137], v[182:185], v[30:33]
	v_mfma_f32_16x16x32_bf16 v[26:29], v[142:145], v[182:185], v[26:29]
	v_mfma_f32_16x16x32_bf16 v[14:17], v[134:137], v[206:209], v[14:17]
	v_mfma_f32_16x16x32_bf16 v[10:13], v[142:145], v[206:209], v[10:13]
	s_setprio 0
	s_setprio 1
	v_mfma_f32_16x16x32_bf16 v[54:57], v[146:149], v[162:165], v[54:57]
	v_mfma_f32_16x16x32_bf16 v[50:53], v[154:157], v[162:165], v[50:53]
	v_mfma_f32_16x16x32_bf16 v[38:41], v[146:149], v[170:173], v[38:41]
	v_mfma_f32_16x16x32_bf16 v[34:37], v[154:157], v[170:173], v[34:37]
	v_mfma_f32_16x16x32_bf16 v[22:25], v[146:149], v[178:181], v[22:25]
	v_mfma_f32_16x16x32_bf16 v[18:21], v[154:157], v[178:181], v[18:21]
	v_mfma_f32_16x16x32_bf16 v[6:9], v[146:149], v[196:199], v[6:9]
	v_mfma_f32_16x16x32_bf16 v[2:5], v[154:157], v[196:199], v[2:5]
	v_mfma_f32_16x16x32_bf16 v[54:57], v[150:153], v[166:169], v[54:57]
	v_mfma_f32_16x16x32_bf16 v[50:53], v[158:161], v[166:169], v[50:53]
	v_mfma_f32_16x16x32_bf16 v[38:41], v[150:153], v[174:177], v[38:41]
	v_mfma_f32_16x16x32_bf16 v[34:37], v[158:161], v[174:177], v[34:37]
	v_mfma_f32_16x16x32_bf16 v[22:25], v[150:153], v[182:185], v[22:25]
	v_mfma_f32_16x16x32_bf16 v[18:21], v[158:161], v[182:185], v[18:21]
	v_mfma_f32_16x16x32_bf16 v[6:9], v[150:153], v[206:209], v[6:9]
	v_mfma_f32_16x16x32_bf16 v[2:5], v[158:161], v[206:209], v[2:5]
	s_barrier
	s_setprio 0
	s_add_i32 s90, 0, 0x18000
	s_add_i32 s91, 0, 0x1c000
	v_add_u32_e32 v142, s90, v220
	v_add_u32_e32 v158, s91, v220
	ds_read_b128 v[130:133], v142
	ds_read_b128 v[134:137], v142 offset:1024
	ds_read_b128 v[138:141], v142 offset:2048
	ds_read_b128 v[142:145], v142 offset:3072
	ds_read_b128 v[146:149], v158
	ds_read_b128 v[150:153], v158 offset:1024
	ds_read_b128 v[154:157], v158 offset:2048
	ds_read_b128 v[158:161], v158 offset:3072
	s_add_u32 s52, s52, 0x80000
	s_addc_u32 s53, s53, 0
	s_mov_b32 m0, s57
	v_lshl_add_u64 v[218:219], s[52:53], 0, v[186:187]
	ds_read_b128 v[162:165], v222 offset:32768
	ds_read_b128 v[166:169], v222 offset:33792
	ds_read_b128 v[170:173], v222 offset:34816
	ds_read_b128 v[174:177], v222 offset:35840
	ds_read_b128 v[178:181], v222 offset:36864
	ds_read_b128 v[182:185], v222 offset:37888
	ds_read_b128 v[196:199], v222 offset:38912
	ds_read_b128 v[206:209], v222 offset:39936
	global_load_lds_dwordx4 v[218:219], off
	s_mov_b32 m0, s60
	v_lshl_add_u64 v[218:219], s[52:53], 0, v[188:189]
	global_load_lds_dwordx4 v[218:219], off
	s_waitcnt vmcnt(8) lgkmcnt(0)
	s_setprio 1
	s_barrier
	v_mfma_f32_16x16x32_bf16 v[126:129], v[130:133], v[162:165], v[126:129]
	v_mfma_f32_16x16x32_bf16 v[122:125], v[138:141], v[162:165], v[122:125]
	v_mfma_f32_16x16x32_bf16 v[110:113], v[130:133], v[170:173], v[110:113]
	v_mfma_f32_16x16x32_bf16 v[106:109], v[138:141], v[170:173], v[106:109]
	v_mfma_f32_16x16x32_bf16 v[94:97], v[130:133], v[178:181], v[94:97]
	v_mfma_f32_16x16x32_bf16 v[90:93], v[138:141], v[178:181], v[90:93]
	v_mfma_f32_16x16x32_bf16 v[78:81], v[130:133], v[196:199], v[78:81]
	v_mfma_f32_16x16x32_bf16 v[74:77], v[138:141], v[196:199], v[74:77]
	v_mfma_f32_16x16x32_bf16 v[126:129], v[134:137], v[166:169], v[126:129]
	v_mfma_f32_16x16x32_bf16 v[122:125], v[142:145], v[166:169], v[122:125]
	v_mfma_f32_16x16x32_bf16 v[110:113], v[134:137], v[174:177], v[110:113]
	v_mfma_f32_16x16x32_bf16 v[106:109], v[142:145], v[174:177], v[106:109]
	v_mfma_f32_16x16x32_bf16 v[94:97], v[134:137], v[182:185], v[94:97]
	v_mfma_f32_16x16x32_bf16 v[90:93], v[142:145], v[182:185], v[90:93]
	v_mfma_f32_16x16x32_bf16 v[78:81], v[134:137], v[206:209], v[78:81]
	v_mfma_f32_16x16x32_bf16 v[74:77], v[142:145], v[206:209], v[74:77]
	s_setprio 0
	s_setprio 1
	v_mfma_f32_16x16x32_bf16 v[118:121], v[146:149], v[162:165], v[118:121]
	v_mfma_f32_16x16x32_bf16 v[114:117], v[154:157], v[162:165], v[114:117]
	v_mfma_f32_16x16x32_bf16 v[102:105], v[146:149], v[170:173], v[102:105]
	v_mfma_f32_16x16x32_bf16 v[98:101], v[154:157], v[170:173], v[98:101]
	v_mfma_f32_16x16x32_bf16 v[86:89], v[146:149], v[178:181], v[86:89]
	v_mfma_f32_16x16x32_bf16 v[82:85], v[154:157], v[178:181], v[82:85]
	v_mfma_f32_16x16x32_bf16 v[70:73], v[146:149], v[196:199], v[70:73]
	v_mfma_f32_16x16x32_bf16 v[66:69], v[154:157], v[196:199], v[66:69]
	v_mfma_f32_16x16x32_bf16 v[118:121], v[150:153], v[166:169], v[118:121]
	v_mfma_f32_16x16x32_bf16 v[114:117], v[158:161], v[166:169], v[114:117]
	v_mfma_f32_16x16x32_bf16 v[102:105], v[150:153], v[174:177], v[102:105]
	v_mfma_f32_16x16x32_bf16 v[98:101], v[158:161], v[174:177], v[98:101]
	v_mfma_f32_16x16x32_bf16 v[86:89], v[150:153], v[182:185], v[86:89]
	v_mfma_f32_16x16x32_bf16 v[82:85], v[158:161], v[182:185], v[82:85]
	v_mfma_f32_16x16x32_bf16 v[70:73], v[150:153], v[206:209], v[70:73]
	v_mfma_f32_16x16x32_bf16 v[66:69], v[158:161], v[206:209], v[66:69]
	s_barrier
	s_setprio 0
	s_add_i32 s52, s90, s47
	v_lshl_add_u64 v[210:211], v[210:211], 0, s[58:59]
	s_mov_b32 m0, s52
	ds_read_b128 v[162:165], v222 offset:49152
	ds_read_b128 v[166:169], v222 offset:50176
	ds_read_b128 v[170:173], v222 offset:51200
	ds_read_b128 v[174:177], v222 offset:52224
	ds_read_b128 v[178:181], v222 offset:53248
	ds_read_b128 v[182:185], v222 offset:54272
	ds_read_b128 v[196:199], v222 offset:55296
	ds_read_b128 v[206:209], v222 offset:56320
	global_load_lds_dwordx4 v[210:211], off
	s_add_i32 m0, s52, 0x2000
	s_add_u32 s34, s34, 0x80080
	v_lshl_add_u64 v[210:211], v[212:213], 0, s[58:59]
	s_addc_u32 s35, s35, 0
	s_add_i32 s52, s91, s47
	global_load_lds_dwordx4 v[210:211], off
	s_mov_b32 m0, s52
	v_lshl_add_u64 v[210:211], s[34:35], 0, v[190:191]
	global_load_lds_dwordx4 v[210:211], off
	s_add_i32 m0, s52, 0x2000
	v_lshl_add_u64 v[210:211], s[34:35], 0, v[200:201]
	global_load_lds_dwordx4 v[210:211], off
	s_mov_b32 m0, s61
	v_lshl_add_u64 v[210:211], v[214:215], 0, s[58:59]
	global_load_lds_dwordx4 v[210:211], off
	s_mov_b32 m0, s69
	v_lshl_add_u64 v[210:211], v[216:217], 0, s[58:59]
	global_load_lds_dwordx4 v[210:211], off
	s_waitcnt vmcnt(8) lgkmcnt(0)
	s_setprio 1
	s_barrier
	v_mfma_f32_16x16x32_bf16 v[62:65], v[130:133], v[162:165], v[62:65]
	v_mfma_f32_16x16x32_bf16 v[58:61], v[138:141], v[162:165], v[58:61]
	v_mfma_f32_16x16x32_bf16 v[46:49], v[130:133], v[170:173], v[46:49]
	v_mfma_f32_16x16x32_bf16 v[42:45], v[138:141], v[170:173], v[42:45]
	v_mfma_f32_16x16x32_bf16 v[30:33], v[130:133], v[178:181], v[30:33]
	v_mfma_f32_16x16x32_bf16 v[26:29], v[138:141], v[178:181], v[26:29]
	v_mfma_f32_16x16x32_bf16 v[14:17], v[130:133], v[196:199], v[14:17]
	v_mfma_f32_16x16x32_bf16 v[10:13], v[138:141], v[196:199], v[10:13]
	v_mfma_f32_16x16x32_bf16 v[62:65], v[134:137], v[166:169], v[62:65]
	v_mfma_f32_16x16x32_bf16 v[58:61], v[142:145], v[166:169], v[58:61]
	v_mfma_f32_16x16x32_bf16 v[46:49], v[134:137], v[174:177], v[46:49]
	v_mfma_f32_16x16x32_bf16 v[42:45], v[142:145], v[174:177], v[42:45]
	v_mfma_f32_16x16x32_bf16 v[30:33], v[134:137], v[182:185], v[30:33]
	v_mfma_f32_16x16x32_bf16 v[26:29], v[142:145], v[182:185], v[26:29]
	v_mfma_f32_16x16x32_bf16 v[14:17], v[134:137], v[206:209], v[14:17]
	v_mfma_f32_16x16x32_bf16 v[10:13], v[142:145], v[206:209], v[10:13]
	s_setprio 0
	s_setprio 1
	v_mfma_f32_16x16x32_bf16 v[54:57], v[146:149], v[162:165], v[54:57]
	v_mfma_f32_16x16x32_bf16 v[50:53], v[154:157], v[162:165], v[50:53]
	v_mfma_f32_16x16x32_bf16 v[38:41], v[146:149], v[170:173], v[38:41]
	v_mfma_f32_16x16x32_bf16 v[34:37], v[154:157], v[170:173], v[34:37]
	v_mfma_f32_16x16x32_bf16 v[22:25], v[146:149], v[178:181], v[22:25]
	v_mfma_f32_16x16x32_bf16 v[18:21], v[154:157], v[178:181], v[18:21]
	v_mfma_f32_16x16x32_bf16 v[6:9], v[146:149], v[196:199], v[6:9]
	v_mfma_f32_16x16x32_bf16 v[2:5], v[154:157], v[196:199], v[2:5]
	v_mfma_f32_16x16x32_bf16 v[54:57], v[150:153], v[166:169], v[54:57]
	v_mfma_f32_16x16x32_bf16 v[50:53], v[158:161], v[166:169], v[50:53]
	v_mfma_f32_16x16x32_bf16 v[38:41], v[150:153], v[174:177], v[38:41]
	v_mfma_f32_16x16x32_bf16 v[34:37], v[158:161], v[174:177], v[34:37]
	v_mfma_f32_16x16x32_bf16 v[22:25], v[150:153], v[182:185], v[22:25]
	v_mfma_f32_16x16x32_bf16 v[18:21], v[158:161], v[182:185], v[18:21]
	v_mfma_f32_16x16x32_bf16 v[6:9], v[150:153], v[206:209], v[6:9]
	v_mfma_f32_16x16x32_bf16 v[2:5], v[158:161], v[206:209], v[2:5]
	s_barrier
	s_setprio 0
	s_add_i32 s89, s89, 2
	s_add_u32 s30, s30, 0x100
	s_addc_u32 s31, s31, 0
	s_add_u32 s81, s81, 0x100
	s_addc_u32 s88, s88, 0
	s_cmp_gt_u32 s89, 29
	s_cbranch_scc0 .LBB0_823

.LBB0_938:
	s_add_u32 s30, s28, 0xfff80080
	s_addc_u32 s31, s29, -1
	s_add_i32 s60, 0, 0x10000
	s_cmp_eq_u32 s57, 28
	s_cselect_b32 s35, s11, s31
	s_cselect_b32 s34, s23, s30
	s_cselect_b32 s31, s21, s56
	s_cselect_b32 s30, s53, s55
	s_add_i32 s66, 0, 0x14000
	v_add_u32_e32 v154, s60, v139
	v_add_u32_e32 v170, s66, v139
	ds_read_b128 v[142:145], v154
	ds_read_b128 v[146:149], v154 offset:1024
	ds_read_b128 v[150:153], v154 offset:2048
	ds_read_b128 v[154:157], v154 offset:3072
	ds_read_b128 v[158:161], v170
	ds_read_b128 v[162:165], v170 offset:1024
	ds_read_b128 v[166:169], v170 offset:2048
	ds_read_b128 v[170:173], v170 offset:3072
	v_lshl_add_u64 v[186:187], s[28:29], 0, v[134:135]
	s_add_i32 m0, s13, 0xc000
	ds_read_b128 v[174:177], v141
	ds_read_b128 v[178:181], v141 offset:1024
	ds_read_b128 v[182:185], v141 offset:2048
	ds_read_b128 v[196:199], v141 offset:3072
	ds_read_b128 v[200:203], v141 offset:4096
	ds_read_b128 v[204:207], v141 offset:5120
	ds_read_b128 v[208:211], v141 offset:6144
	ds_read_b128 v[212:215], v141 offset:7168
	global_load_lds_dwordx4 v[186:187], off
	s_add_i32 m0, s13, 0xe000
	v_lshl_add_u64 v[186:187], s[28:29], 0, v[136:137]
	global_load_lds_dwordx4 v[186:187], off
	s_waitcnt vmcnt(8) lgkmcnt(0)
	s_setprio 1
	s_barrier
	v_mfma_f32_16x16x32_bf16 v[124:127], v[142:145], v[174:177], v[124:127]
	v_mfma_f32_16x16x32_bf16 v[120:123], v[150:153], v[174:177], v[120:123]
	v_mfma_f32_16x16x32_bf16 v[116:119], v[142:145], v[182:185], v[116:119]
	v_mfma_f32_16x16x32_bf16 v[112:115], v[150:153], v[182:185], v[112:115]
	v_mfma_f32_16x16x32_bf16 v[100:103], v[142:145], v[200:203], v[100:103]
	v_mfma_f32_16x16x32_bf16 v[96:99], v[150:153], v[200:203], v[96:99]
	v_mfma_f32_16x16x32_bf16 v[84:87], v[142:145], v[208:211], v[84:87]
	v_mfma_f32_16x16x32_bf16 v[80:83], v[150:153], v[208:211], v[80:83]
	v_mfma_f32_16x16x32_bf16 v[124:127], v[146:149], v[178:181], v[124:127]
	v_mfma_f32_16x16x32_bf16 v[120:123], v[154:157], v[178:181], v[120:123]
	v_mfma_f32_16x16x32_bf16 v[116:119], v[146:149], v[196:199], v[116:119]
	v_mfma_f32_16x16x32_bf16 v[112:115], v[154:157], v[196:199], v[112:115]
	v_mfma_f32_16x16x32_bf16 v[100:103], v[146:149], v[204:207], v[100:103]
	v_mfma_f32_16x16x32_bf16 v[96:99], v[154:157], v[204:207], v[96:99]
	v_mfma_f32_16x16x32_bf16 v[84:87], v[146:149], v[212:215], v[84:87]
	v_mfma_f32_16x16x32_bf16 v[80:83], v[154:157], v[212:215], v[80:83]
	s_setprio 0
	s_setprio 1
	v_mfma_f32_16x16x32_bf16 v[108:111], v[158:161], v[174:177], v[108:111]
	v_mfma_f32_16x16x32_bf16 v[104:107], v[166:169], v[174:177], v[104:107]
	v_mfma_f32_16x16x32_bf16 v[92:95], v[158:161], v[182:185], v[92:95]
	v_mfma_f32_16x16x32_bf16 v[88:91], v[166:169], v[182:185], v[88:91]
	v_mfma_f32_16x16x32_bf16 v[76:79], v[158:161], v[200:203], v[76:79]
	v_mfma_f32_16x16x32_bf16 v[72:75], v[166:169], v[200:203], v[72:75]
	v_mfma_f32_16x16x32_bf16 v[68:71], v[158:161], v[208:211], v[68:71]
	v_mfma_f32_16x16x32_bf16 v[64:67], v[166:169], v[208:211], v[64:67]
	v_mfma_f32_16x16x32_bf16 v[108:111], v[162:165], v[178:181], v[108:111]
	v_mfma_f32_16x16x32_bf16 v[104:107], v[170:173], v[178:181], v[104:107]
	v_mfma_f32_16x16x32_bf16 v[92:95], v[162:165], v[196:199], v[92:95]
	v_mfma_f32_16x16x32_bf16 v[88:91], v[170:173], v[196:199], v[88:91]
	v_mfma_f32_16x16x32_bf16 v[76:79], v[162:165], v[204:207], v[76:79]
	v_mfma_f32_16x16x32_bf16 v[72:75], v[170:173], v[204:207], v[72:75]
	v_mfma_f32_16x16x32_bf16 v[68:71], v[162:165], v[212:215], v[68:71]
	v_mfma_f32_16x16x32_bf16 v[64:67], v[170:173], v[212:215], v[64:67]
	s_barrier
	s_setprio 0
	s_add_i32 s60, s60, s38
	v_lshl_add_u64 v[186:187], s[30:31], 0, v[190:191]
	s_mov_b32 m0, s60
	ds_read_b128 v[174:177], v141 offset:16384
	ds_read_b128 v[178:181], v141 offset:17408
	ds_read_b128 v[182:185], v141 offset:18432
	ds_read_b128 v[196:199], v141 offset:19456
	ds_read_b128 v[200:203], v141 offset:20480
	ds_read_b128 v[204:207], v141 offset:21504
	ds_read_b128 v[208:211], v141 offset:22528
	ds_read_b128 v[212:215], v141 offset:23552
	global_load_lds_dwordx4 v[186:187], off
	s_add_i32 m0, s60, 0x2000
	s_add_u32 s60, s30, 0x80000
	v_lshl_add_u64 v[216:217], s[30:31], 0, v[132:133]
	s_addc_u32 s61, s31, 0
	s_add_i32 s66, s66, s38
	global_load_lds_dwordx4 v[216:217], off
	v_lshl_add_u64 v[218:219], s[60:61], 0, v[190:191]
	s_mov_b32 m0, s66
	v_lshl_add_u64 v[220:221], s[34:35], 0, v[130:131]
	global_load_lds_dwordx4 v[218:219], off
	s_add_i32 m0, s66, 0x2000
	v_lshl_add_u64 v[218:219], s[60:61], 0, v[132:133]
	global_load_lds_dwordx4 v[218:219], off
	s_mov_b32 m0, s13
	v_lshl_add_u64 v[218:219], s[34:35], 0, v[128:129]
	global_load_lds_dwordx4 v[218:219], off
	s_mov_b32 m0, s39
	s_nop 0
	global_load_lds_dwordx4 v[220:221], off
	s_waitcnt vmcnt(8) lgkmcnt(0)
	s_setprio 1
	s_barrier
	v_mfma_f32_16x16x32_bf16 v[60:63], v[142:145], v[174:177], v[60:63]
	v_mfma_f32_16x16x32_bf16 v[56:59], v[150:153], v[174:177], v[56:59]
	v_mfma_f32_16x16x32_bf16 v[52:55], v[142:145], v[182:185], v[52:55]
	v_mfma_f32_16x16x32_bf16 v[48:51], v[150:153], v[182:185], v[48:51]
	v_mfma_f32_16x16x32_bf16 v[36:39], v[142:145], v[200:203], v[36:39]
	v_mfma_f32_16x16x32_bf16 v[32:35], v[150:153], v[200:203], v[32:35]
	v_mfma_f32_16x16x32_bf16 v[20:23], v[142:145], v[208:211], v[20:23]
	v_mfma_f32_16x16x32_bf16 v[16:19], v[150:153], v[208:211], v[16:19]
	v_mfma_f32_16x16x32_bf16 v[60:63], v[146:149], v[178:181], v[60:63]
	v_mfma_f32_16x16x32_bf16 v[56:59], v[154:157], v[178:181], v[56:59]
	v_mfma_f32_16x16x32_bf16 v[52:55], v[146:149], v[196:199], v[52:55]
	v_mfma_f32_16x16x32_bf16 v[48:51], v[154:157], v[196:199], v[48:51]
	v_mfma_f32_16x16x32_bf16 v[36:39], v[146:149], v[204:207], v[36:39]
	v_mfma_f32_16x16x32_bf16 v[32:35], v[154:157], v[204:207], v[32:35]
	v_mfma_f32_16x16x32_bf16 v[20:23], v[146:149], v[212:215], v[20:23]
	v_mfma_f32_16x16x32_bf16 v[16:19], v[154:157], v[212:215], v[16:19]
	s_setprio 0
	s_setprio 1
	v_mfma_f32_16x16x32_bf16 v[44:47], v[158:161], v[174:177], v[44:47]
	v_mfma_f32_16x16x32_bf16 v[40:43], v[166:169], v[174:177], v[40:43]
	v_mfma_f32_16x16x32_bf16 v[28:31], v[158:161], v[182:185], v[28:31]
	v_mfma_f32_16x16x32_bf16 v[24:27], v[166:169], v[182:185], v[24:27]
	v_mfma_f32_16x16x32_bf16 v[12:15], v[158:161], v[200:203], v[12:15]
	v_mfma_f32_16x16x32_bf16 v[8:11], v[166:169], v[200:203], v[8:11]
	v_mfma_f32_16x16x32_bf16 v[4:7], v[158:161], v[208:211], v[4:7]
	v_mfma_f32_16x16x32_bf16 v[0:3], v[166:169], v[208:211], v[0:3]
	v_mfma_f32_16x16x32_bf16 v[44:47], v[162:165], v[178:181], v[44:47]
	v_mfma_f32_16x16x32_bf16 v[40:43], v[170:173], v[178:181], v[40:43]
	v_mfma_f32_16x16x32_bf16 v[28:31], v[162:165], v[196:199], v[28:31]
	v_mfma_f32_16x16x32_bf16 v[24:27], v[170:173], v[196:199], v[24:27]
	v_mfma_f32_16x16x32_bf16 v[12:15], v[162:165], v[204:207], v[12:15]
	v_mfma_f32_16x16x32_bf16 v[8:11], v[170:173], v[204:207], v[8:11]
	v_mfma_f32_16x16x32_bf16 v[4:7], v[162:165], v[212:215], v[4:7]
	v_mfma_f32_16x16x32_bf16 v[0:3], v[170:173], v[212:215], v[0:3]
	s_barrier
	s_setprio 0
	s_add_i32 s60, 0, 0x18000
	s_add_i32 s61, 0, 0x1c000
	v_add_u32_e32 v154, s60, v139
	v_add_u32_e32 v170, s61, v139
	ds_read_b128 v[142:145], v154
	ds_read_b128 v[146:149], v154 offset:1024
	ds_read_b128 v[150:153], v154 offset:2048
	ds_read_b128 v[154:157], v154 offset:3072
	ds_read_b128 v[158:161], v170
	ds_read_b128 v[162:165], v170 offset:1024
	ds_read_b128 v[166:169], v170 offset:2048
	ds_read_b128 v[170:173], v170 offset:3072
	s_add_u32 s34, s34, 0x80000
	s_addc_u32 s35, s35, 0
	s_mov_b32 m0, s41
	v_lshl_add_u64 v[222:223], s[34:35], 0, v[128:129]
	ds_read_b128 v[174:177], v141 offset:32768
	ds_read_b128 v[178:181], v141 offset:33792
	ds_read_b128 v[182:185], v141 offset:34816
	ds_read_b128 v[196:199], v141 offset:35840
	ds_read_b128 v[200:203], v141 offset:36864
	ds_read_b128 v[204:207], v141 offset:37888
	ds_read_b128 v[208:211], v141 offset:38912
	ds_read_b128 v[212:215], v141 offset:39936
	global_load_lds_dwordx4 v[222:223], off
	s_mov_b32 m0, s42
	v_lshl_add_u64 v[222:223], s[34:35], 0, v[130:131]
	global_load_lds_dwordx4 v[222:223], off
	s_waitcnt vmcnt(8) lgkmcnt(0)
	s_setprio 1
	s_barrier
	v_mfma_f32_16x16x32_bf16 v[124:127], v[142:145], v[174:177], v[124:127]
	v_mfma_f32_16x16x32_bf16 v[120:123], v[150:153], v[174:177], v[120:123]
	v_mfma_f32_16x16x32_bf16 v[116:119], v[142:145], v[182:185], v[116:119]
	v_mfma_f32_16x16x32_bf16 v[112:115], v[150:153], v[182:185], v[112:115]
	v_mfma_f32_16x16x32_bf16 v[100:103], v[142:145], v[200:203], v[100:103]
	v_mfma_f32_16x16x32_bf16 v[96:99], v[150:153], v[200:203], v[96:99]
	v_mfma_f32_16x16x32_bf16 v[84:87], v[142:145], v[208:211], v[84:87]
	v_mfma_f32_16x16x32_bf16 v[80:83], v[150:153], v[208:211], v[80:83]
	v_mfma_f32_16x16x32_bf16 v[124:127], v[146:149], v[178:181], v[124:127]
	v_mfma_f32_16x16x32_bf16 v[120:123], v[154:157], v[178:181], v[120:123]
	v_mfma_f32_16x16x32_bf16 v[116:119], v[146:149], v[196:199], v[116:119]
	v_mfma_f32_16x16x32_bf16 v[112:115], v[154:157], v[196:199], v[112:115]
	v_mfma_f32_16x16x32_bf16 v[100:103], v[146:149], v[204:207], v[100:103]
	v_mfma_f32_16x16x32_bf16 v[96:99], v[154:157], v[204:207], v[96:99]
	v_mfma_f32_16x16x32_bf16 v[84:87], v[146:149], v[212:215], v[84:87]
	v_mfma_f32_16x16x32_bf16 v[80:83], v[154:157], v[212:215], v[80:83]
	s_setprio 0
	s_setprio 1
	v_mfma_f32_16x16x32_bf16 v[108:111], v[158:161], v[174:177], v[108:111]
	v_mfma_f32_16x16x32_bf16 v[104:107], v[166:169], v[174:177], v[104:107]
	v_mfma_f32_16x16x32_bf16 v[92:95], v[158:161], v[182:185], v[92:95]
	v_mfma_f32_16x16x32_bf16 v[88:91], v[166:169], v[182:185], v[88:91]
	v_mfma_f32_16x16x32_bf16 v[76:79], v[158:161], v[200:203], v[76:79]
	v_mfma_f32_16x16x32_bf16 v[72:75], v[166:169], v[200:203], v[72:75]
	v_mfma_f32_16x16x32_bf16 v[68:71], v[158:161], v[208:211], v[68:71]
	v_mfma_f32_16x16x32_bf16 v[64:67], v[166:169], v[208:211], v[64:67]
	v_mfma_f32_16x16x32_bf16 v[108:111], v[162:165], v[178:181], v[108:111]
	v_mfma_f32_16x16x32_bf16 v[104:107], v[170:173], v[178:181], v[104:107]
	v_mfma_f32_16x16x32_bf16 v[92:95], v[162:165], v[196:199], v[92:95]
	v_mfma_f32_16x16x32_bf16 v[88:91], v[170:173], v[196:199], v[88:91]
	v_mfma_f32_16x16x32_bf16 v[76:79], v[162:165], v[204:207], v[76:79]
	v_mfma_f32_16x16x32_bf16 v[72:75], v[170:173], v[204:207], v[72:75]
	v_mfma_f32_16x16x32_bf16 v[68:71], v[162:165], v[212:215], v[68:71]
	v_mfma_f32_16x16x32_bf16 v[64:67], v[170:173], v[212:215], v[64:67]
	s_barrier
	s_setprio 0
	s_add_i32 s34, s60, s38
	v_lshl_add_u64 v[186:187], v[186:187], 0, s[58:59]
	s_mov_b32 m0, s34
	ds_read_b128 v[174:177], v141 offset:49152
	ds_read_b128 v[178:181], v141 offset:50176
	ds_read_b128 v[182:185], v141 offset:51200
	ds_read_b128 v[196:199], v141 offset:52224
	ds_read_b128 v[200:203], v141 offset:53248
	ds_read_b128 v[204:207], v141 offset:54272
	ds_read_b128 v[208:211], v141 offset:55296
	ds_read_b128 v[212:215], v141 offset:56320
	global_load_lds_dwordx4 v[186:187], off
	s_add_i32 m0, s34, 0x2000
	s_add_u32 s30, s30, 0x80080
	v_lshl_add_u64 v[186:187], v[216:217], 0, s[58:59]
	s_addc_u32 s31, s31, 0
	s_add_i32 s34, s61, s38
	global_load_lds_dwordx4 v[186:187], off
	s_mov_b32 m0, s34
	v_lshl_add_u64 v[186:187], s[30:31], 0, v[190:191]
	global_load_lds_dwordx4 v[186:187], off
	s_add_i32 m0, s34, 0x2000
	v_lshl_add_u64 v[186:187], s[30:31], 0, v[132:133]
	global_load_lds_dwordx4 v[186:187], off
	s_mov_b32 m0, s43
	v_lshl_add_u64 v[186:187], v[218:219], 0, s[58:59]
	global_load_lds_dwordx4 v[186:187], off
	s_mov_b32 m0, s47
	v_lshl_add_u64 v[186:187], v[220:221], 0, s[58:59]
	global_load_lds_dwordx4 v[186:187], off
	s_waitcnt vmcnt(8) lgkmcnt(0)
	s_setprio 1
	s_barrier
	v_mfma_f32_16x16x32_bf16 v[60:63], v[142:145], v[174:177], v[60:63]
	v_mfma_f32_16x16x32_bf16 v[56:59], v[150:153], v[174:177], v[56:59]
	v_mfma_f32_16x16x32_bf16 v[52:55], v[142:145], v[182:185], v[52:55]
	v_mfma_f32_16x16x32_bf16 v[48:51], v[150:153], v[182:185], v[48:51]
	v_mfma_f32_16x16x32_bf16 v[36:39], v[142:145], v[200:203], v[36:39]
	v_mfma_f32_16x16x32_bf16 v[32:35], v[150:153], v[200:203], v[32:35]
	v_mfma_f32_16x16x32_bf16 v[20:23], v[142:145], v[208:211], v[20:23]
	v_mfma_f32_16x16x32_bf16 v[16:19], v[150:153], v[208:211], v[16:19]
	v_mfma_f32_16x16x32_bf16 v[60:63], v[146:149], v[178:181], v[60:63]
	v_mfma_f32_16x16x32_bf16 v[56:59], v[154:157], v[178:181], v[56:59]
	v_mfma_f32_16x16x32_bf16 v[52:55], v[146:149], v[196:199], v[52:55]
	v_mfma_f32_16x16x32_bf16 v[48:51], v[154:157], v[196:199], v[48:51]
	v_mfma_f32_16x16x32_bf16 v[36:39], v[146:149], v[204:207], v[36:39]
	v_mfma_f32_16x16x32_bf16 v[32:35], v[154:157], v[204:207], v[32:35]
	v_mfma_f32_16x16x32_bf16 v[20:23], v[146:149], v[212:215], v[20:23]
	v_mfma_f32_16x16x32_bf16 v[16:19], v[154:157], v[212:215], v[16:19]
	s_setprio 0
	s_setprio 1
	v_mfma_f32_16x16x32_bf16 v[44:47], v[158:161], v[174:177], v[44:47]
	v_mfma_f32_16x16x32_bf16 v[40:43], v[166:169], v[174:177], v[40:43]
	v_mfma_f32_16x16x32_bf16 v[28:31], v[158:161], v[182:185], v[28:31]
	v_mfma_f32_16x16x32_bf16 v[24:27], v[166:169], v[182:185], v[24:27]
	v_mfma_f32_16x16x32_bf16 v[12:15], v[158:161], v[200:203], v[12:15]
	v_mfma_f32_16x16x32_bf16 v[8:11], v[166:169], v[200:203], v[8:11]
	v_mfma_f32_16x16x32_bf16 v[4:7], v[158:161], v[208:211], v[4:7]
	v_mfma_f32_16x16x32_bf16 v[0:3], v[166:169], v[208:211], v[0:3]
	v_mfma_f32_16x16x32_bf16 v[44:47], v[162:165], v[178:181], v[44:47]
	v_mfma_f32_16x16x32_bf16 v[40:43], v[170:173], v[178:181], v[40:43]
	v_mfma_f32_16x16x32_bf16 v[28:31], v[162:165], v[196:199], v[28:31]
	v_mfma_f32_16x16x32_bf16 v[24:27], v[170:173], v[196:199], v[24:27]
	v_mfma_f32_16x16x32_bf16 v[12:15], v[162:165], v[204:207], v[12:15]
	v_mfma_f32_16x16x32_bf16 v[8:11], v[170:173], v[204:207], v[8:11]
	v_mfma_f32_16x16x32_bf16 v[4:7], v[162:165], v[212:215], v[4:7]
	v_mfma_f32_16x16x32_bf16 v[0:3], v[170:173], v[212:215], v[0:3]
	s_barrier
	s_setprio 0
	s_add_i32 s57, s57, 2
	s_add_u32 s28, s28, 0x100
	s_addc_u32 s29, s29, 0
	s_add_u32 s55, s55, 0x100
	s_addc_u32 s56, s56, 0
	s_cmp_gt_u32 s57, 29
	s_cbranch_scc0 .LBB0_938

.LBB0_1105:
	s_add_u32 s16, s10, 0x100
	s_addc_u32 s17, s11, 0
	s_add_i32 vcc_hi, 0, 0x10000
	s_cmp_eq_u32 vcc_lo, 28
	s_cselect_b32 s69, s13, s17
	s_cselect_b32 s68, s15, s16
	s_cselect_b32 s53, s57, s67
	s_cselect_b32 s52, s61, s66
	s_add_i32 s0, 0, 0x14000
	v_add_u32_e32 v140, vcc_hi, v200
	v_add_u32_e32 v156, s0, v200
	ds_read_b128 v[128:131], v140
	ds_read_b128 v[132:135], v140 offset:1024
	ds_read_b128 v[136:139], v140 offset:2048
	ds_read_b128 v[140:143], v140 offset:3072
	ds_read_b128 v[144:147], v156
	ds_read_b128 v[148:151], v156 offset:1024
	ds_read_b128 v[152:155], v156 offset:2048
	ds_read_b128 v[156:159], v156 offset:3072
	v_lshl_add_u64 v[186:187], s[10:11], 0, v[182:183]
	s_add_i32 m0, s40, 0xc000
	ds_read_b128 v[160:163], v206
	ds_read_b128 v[164:167], v206 offset:1024
	ds_read_b128 v[168:171], v206 offset:2048
	ds_read_b128 v[172:175], v206 offset:3072
	ds_read_b128 v[196:199], v206 offset:4096
	ds_read_b128 v[208:211], v206 offset:5120
	ds_read_b128 v[212:215], v206 offset:6144
	ds_read_b128 v[216:219], v206 offset:7168
	global_load_lds_dwordx4 v[186:187], off
	s_add_i32 m0, s40, 0xe000
	v_lshl_add_u64 v[186:187], s[10:11], 0, v[184:185]
	global_load_lds_dwordx4 v[186:187], off
	s_waitcnt vmcnt(8) lgkmcnt(0)
	s_setprio 1
	s_barrier
	v_mfma_f32_16x16x32_bf16 v[120:123], v[128:131], v[160:163], v[120:123]
	v_mfma_f32_16x16x32_bf16 v[48:51], v[136:139], v[160:163], v[48:51]
	v_mfma_f32_16x16x32_bf16 v[124:127], v[128:131], v[168:171], v[124:127]
	v_mfma_f32_16x16x32_bf16 v[60:63], v[136:139], v[168:171], v[60:63]
	v_mfma_f32_16x16x32_bf16 v[112:115], v[128:131], v[196:199], v[112:115]
	v_mfma_f32_16x16x32_bf16 v[52:55], v[136:139], v[196:199], v[52:55]
	v_mfma_f32_16x16x32_bf16 v[108:111], v[128:131], v[212:215], v[108:111]
	v_mfma_f32_16x16x32_bf16 v[36:39], v[136:139], v[212:215], v[36:39]
	v_mfma_f32_16x16x32_bf16 v[120:123], v[132:135], v[164:167], v[120:123]
	v_mfma_f32_16x16x32_bf16 v[48:51], v[140:143], v[164:167], v[48:51]
	v_mfma_f32_16x16x32_bf16 v[124:127], v[132:135], v[172:175], v[124:127]
	v_mfma_f32_16x16x32_bf16 v[60:63], v[140:143], v[172:175], v[60:63]
	v_mfma_f32_16x16x32_bf16 v[112:115], v[132:135], v[208:211], v[112:115]
	v_mfma_f32_16x16x32_bf16 v[52:55], v[140:143], v[208:211], v[52:55]
	v_mfma_f32_16x16x32_bf16 v[108:111], v[132:135], v[216:219], v[108:111]
	v_mfma_f32_16x16x32_bf16 v[36:39], v[140:143], v[216:219], v[36:39]
	s_setprio 0
	s_setprio 1
	v_mfma_f32_16x16x32_bf16 v[100:103], v[144:147], v[160:163], v[100:103]
	v_mfma_f32_16x16x32_bf16 v[40:43], v[152:155], v[160:163], v[40:43]
	v_mfma_f32_16x16x32_bf16 v[116:119], v[144:147], v[168:171], v[116:119]
	v_mfma_f32_16x16x32_bf16 v[56:59], v[152:155], v[168:171], v[56:59]
	v_mfma_f32_16x16x32_bf16 v[104:107], v[144:147], v[196:199], v[104:107]
	v_mfma_f32_16x16x32_bf16 v[44:47], v[152:155], v[196:199], v[44:47]
	v_mfma_f32_16x16x32_bf16 v[96:99], v[144:147], v[212:215], v[96:99]
	v_mfma_f32_16x16x32_bf16 v[32:35], v[152:155], v[212:215], v[32:35]
	v_mfma_f32_16x16x32_bf16 v[100:103], v[148:151], v[164:167], v[100:103]
	v_mfma_f32_16x16x32_bf16 v[40:43], v[156:159], v[164:167], v[40:43]
	v_mfma_f32_16x16x32_bf16 v[116:119], v[148:151], v[172:175], v[116:119]
	v_mfma_f32_16x16x32_bf16 v[56:59], v[156:159], v[172:175], v[56:59]
	v_mfma_f32_16x16x32_bf16 v[104:107], v[148:151], v[208:211], v[104:107]
	v_mfma_f32_16x16x32_bf16 v[44:47], v[156:159], v[208:211], v[44:47]
	v_mfma_f32_16x16x32_bf16 v[96:99], v[148:151], v[216:219], v[96:99]
	v_mfma_f32_16x16x32_bf16 v[32:35], v[156:159], v[216:219], v[32:35]
	s_barrier
	s_setprio 0
	s_add_i32 s1, vcc_hi, s33
	v_lshl_add_u64 v[186:187], s[52:53], 0, v[190:191]
	s_mov_b32 m0, s1
	ds_read_b128 v[160:163], v206 offset:16384
	ds_read_b128 v[164:167], v206 offset:17408
	ds_read_b128 v[168:171], v206 offset:18432
	ds_read_b128 v[172:175], v206 offset:19456
	ds_read_b128 v[196:199], v206 offset:20480
	ds_read_b128 v[208:211], v206 offset:21504
	ds_read_b128 v[212:215], v206 offset:22528
	ds_read_b128 v[216:219], v206 offset:23552
	global_load_lds_dwordx4 v[186:187], off
	s_add_i32 m0, s1, 0x2000
	s_add_u32 s10, s52, 0x80000
	v_lshl_add_u64 v[220:221], s[52:53], 0, v[180:181]
	s_addc_u32 s11, s53, 0
	s_add_i32 s0, s0, s33
	global_load_lds_dwordx4 v[220:221], off
	v_lshl_add_u64 v[222:223], s[10:11], 0, v[190:191]
	s_mov_b32 m0, s0
	v_lshl_add_u64 v[224:225], s[68:69], 0, v[178:179]
	global_load_lds_dwordx4 v[222:223], off
	s_add_i32 m0, s0, 0x2000
	v_lshl_add_u64 v[222:223], s[10:11], 0, v[180:181]
	global_load_lds_dwordx4 v[222:223], off
	s_mov_b32 m0, s40
	v_lshl_add_u64 v[222:223], s[68:69], 0, v[176:177]
	global_load_lds_dwordx4 v[222:223], off
	s_mov_b32 m0, s41
	s_nop 0
	global_load_lds_dwordx4 v[224:225], off
	s_waitcnt vmcnt(8) lgkmcnt(0)
	s_setprio 1
	s_barrier
	v_mfma_f32_16x16x32_bf16 v[88:91], v[128:131], v[160:163], v[88:91]
	v_mfma_f32_16x16x32_bf16 v[20:23], v[136:139], v[160:163], v[20:23]
	v_mfma_f32_16x16x32_bf16 v[92:95], v[128:131], v[168:171], v[92:95]
	v_mfma_f32_16x16x32_bf16 v[28:31], v[136:139], v[168:171], v[28:31]
	v_mfma_f32_16x16x32_bf16 v[80:83], v[128:131], v[196:199], v[80:83]
	v_mfma_f32_16x16x32_bf16 v[16:19], v[136:139], v[196:199], v[16:19]
	v_mfma_f32_16x16x32_bf16 v[76:79], v[128:131], v[212:215], v[76:79]
	v_mfma_f32_16x16x32_bf16 v[12:15], v[136:139], v[212:215], v[12:15]
	v_mfma_f32_16x16x32_bf16 v[88:91], v[132:135], v[164:167], v[88:91]
	v_mfma_f32_16x16x32_bf16 v[20:23], v[140:143], v[164:167], v[20:23]
	v_mfma_f32_16x16x32_bf16 v[92:95], v[132:135], v[172:175], v[92:95]
	v_mfma_f32_16x16x32_bf16 v[28:31], v[140:143], v[172:175], v[28:31]
	v_mfma_f32_16x16x32_bf16 v[80:83], v[132:135], v[208:211], v[80:83]
	v_mfma_f32_16x16x32_bf16 v[16:19], v[140:143], v[208:211], v[16:19]
	v_mfma_f32_16x16x32_bf16 v[76:79], v[132:135], v[216:219], v[76:79]
	v_mfma_f32_16x16x32_bf16 v[12:15], v[140:143], v[216:219], v[12:15]
	s_setprio 0
	s_setprio 1
	v_mfma_f32_16x16x32_bf16 v[68:71], v[144:147], v[160:163], v[68:71]
	v_mfma_f32_16x16x32_bf16 v[4:7], v[152:155], v[160:163], v[4:7]
	v_mfma_f32_16x16x32_bf16 v[84:87], v[144:147], v[168:171], v[84:87]
	v_mfma_f32_16x16x32_bf16 v[24:27], v[152:155], v[168:171], v[24:27]
	v_mfma_f32_16x16x32_bf16 v[72:75], v[144:147], v[196:199], v[72:75]
	v_mfma_f32_16x16x32_bf16 v[8:11], v[152:155], v[196:199], v[8:11]
	v_mfma_f32_16x16x32_bf16 v[64:67], v[144:147], v[212:215], v[64:67]
	v_mfma_f32_16x16x32_bf16 v[0:3], v[152:155], v[212:215], v[0:3]
	v_mfma_f32_16x16x32_bf16 v[68:71], v[148:151], v[164:167], v[68:71]
	v_mfma_f32_16x16x32_bf16 v[4:7], v[156:159], v[164:167], v[4:7]
	v_mfma_f32_16x16x32_bf16 v[84:87], v[148:151], v[172:175], v[84:87]
	v_mfma_f32_16x16x32_bf16 v[24:27], v[156:159], v[172:175], v[24:27]
	v_mfma_f32_16x16x32_bf16 v[72:75], v[148:151], v[208:211], v[72:75]
	v_mfma_f32_16x16x32_bf16 v[8:11], v[156:159], v[208:211], v[8:11]
	v_mfma_f32_16x16x32_bf16 v[64:67], v[148:151], v[216:219], v[64:67]
	v_mfma_f32_16x16x32_bf16 v[0:3], v[156:159], v[216:219], v[0:3]
	s_barrier
	s_setprio 0
	s_add_i32 s0, 0, 0x18000
	s_add_i32 s1, 0, 0x1c000
	v_add_u32_e32 v140, s0, v200
	v_add_u32_e32 v156, s1, v200
	ds_read_b128 v[128:131], v140
	ds_read_b128 v[132:135], v140 offset:1024
	ds_read_b128 v[136:139], v140 offset:2048
	ds_read_b128 v[140:143], v140 offset:3072
	ds_read_b128 v[144:147], v156
	ds_read_b128 v[148:151], v156 offset:1024
	ds_read_b128 v[152:155], v156 offset:2048
	ds_read_b128 v[156:159], v156 offset:3072
	s_add_u32 s10, s68, 0x80000
	s_addc_u32 s11, s69, 0
	s_mov_b32 m0, s42
	v_lshl_add_u64 v[226:227], s[10:11], 0, v[176:177]
	ds_read_b128 v[160:163], v206 offset:32768
	ds_read_b128 v[164:167], v206 offset:33792
	ds_read_b128 v[168:171], v206 offset:34816
	ds_read_b128 v[172:175], v206 offset:35840
	ds_read_b128 v[196:199], v206 offset:36864
	ds_read_b128 v[208:211], v206 offset:37888
	ds_read_b128 v[212:215], v206 offset:38912
	ds_read_b128 v[216:219], v206 offset:39936
	global_load_lds_dwordx4 v[226:227], off
	s_mov_b32 m0, s43
	v_lshl_add_u64 v[226:227], s[10:11], 0, v[178:179]
	global_load_lds_dwordx4 v[226:227], off
	s_waitcnt vmcnt(8) lgkmcnt(0)
	s_setprio 1
	s_barrier
	v_mfma_f32_16x16x32_bf16 v[120:123], v[128:131], v[160:163], v[120:123]
	v_mfma_f32_16x16x32_bf16 v[48:51], v[136:139], v[160:163], v[48:51]
	v_mfma_f32_16x16x32_bf16 v[124:127], v[128:131], v[168:171], v[124:127]
	v_mfma_f32_16x16x32_bf16 v[60:63], v[136:139], v[168:171], v[60:63]
	v_mfma_f32_16x16x32_bf16 v[112:115], v[128:131], v[196:199], v[112:115]
	v_mfma_f32_16x16x32_bf16 v[52:55], v[136:139], v[196:199], v[52:55]
	v_mfma_f32_16x16x32_bf16 v[108:111], v[128:131], v[212:215], v[108:111]
	v_mfma_f32_16x16x32_bf16 v[36:39], v[136:139], v[212:215], v[36:39]
	v_mfma_f32_16x16x32_bf16 v[120:123], v[132:135], v[164:167], v[120:123]
	v_mfma_f32_16x16x32_bf16 v[48:51], v[140:143], v[164:167], v[48:51]
	v_mfma_f32_16x16x32_bf16 v[124:127], v[132:135], v[172:175], v[124:127]
	v_mfma_f32_16x16x32_bf16 v[60:63], v[140:143], v[172:175], v[60:63]
	v_mfma_f32_16x16x32_bf16 v[112:115], v[132:135], v[208:211], v[112:115]
	v_mfma_f32_16x16x32_bf16 v[52:55], v[140:143], v[208:211], v[52:55]
	v_mfma_f32_16x16x32_bf16 v[108:111], v[132:135], v[216:219], v[108:111]
	v_mfma_f32_16x16x32_bf16 v[36:39], v[140:143], v[216:219], v[36:39]
	s_setprio 0
	s_setprio 1
	v_mfma_f32_16x16x32_bf16 v[100:103], v[144:147], v[160:163], v[100:103]
	v_mfma_f32_16x16x32_bf16 v[40:43], v[152:155], v[160:163], v[40:43]
	v_mfma_f32_16x16x32_bf16 v[116:119], v[144:147], v[168:171], v[116:119]
	v_mfma_f32_16x16x32_bf16 v[56:59], v[152:155], v[168:171], v[56:59]
	v_mfma_f32_16x16x32_bf16 v[104:107], v[144:147], v[196:199], v[104:107]
	v_mfma_f32_16x16x32_bf16 v[44:47], v[152:155], v[196:199], v[44:47]
	v_mfma_f32_16x16x32_bf16 v[96:99], v[144:147], v[212:215], v[96:99]
	v_mfma_f32_16x16x32_bf16 v[32:35], v[152:155], v[212:215], v[32:35]
	v_mfma_f32_16x16x32_bf16 v[100:103], v[148:151], v[164:167], v[100:103]
	v_mfma_f32_16x16x32_bf16 v[40:43], v[156:159], v[164:167], v[40:43]
	v_mfma_f32_16x16x32_bf16 v[116:119], v[148:151], v[172:175], v[116:119]
	v_mfma_f32_16x16x32_bf16 v[56:59], v[156:159], v[172:175], v[56:59]
	v_mfma_f32_16x16x32_bf16 v[104:107], v[148:151], v[208:211], v[104:107]
	v_mfma_f32_16x16x32_bf16 v[44:47], v[156:159], v[208:211], v[44:47]
	v_mfma_f32_16x16x32_bf16 v[96:99], v[148:151], v[216:219], v[96:99]
	v_mfma_f32_16x16x32_bf16 v[32:35], v[156:159], v[216:219], v[32:35]
	s_barrier
	s_setprio 0
	s_add_i32 s0, s0, s33
	v_lshl_add_u64 v[186:187], v[186:187], 0, s[58:59]
	s_mov_b32 m0, s0
	ds_read_b128 v[160:163], v206 offset:49152
	ds_read_b128 v[164:167], v206 offset:50176
	ds_read_b128 v[168:171], v206 offset:51200
	ds_read_b128 v[172:175], v206 offset:52224
	ds_read_b128 v[196:199], v206 offset:53248
	ds_read_b128 v[208:211], v206 offset:54272
	ds_read_b128 v[212:215], v206 offset:55296
	ds_read_b128 v[216:219], v206 offset:56320
	global_load_lds_dwordx4 v[186:187], off
	s_add_i32 m0, s0, 0x2000
	s_add_u32 s10, s52, 0x80080
	v_lshl_add_u64 v[186:187], v[220:221], 0, s[58:59]
	s_addc_u32 s11, s53, 0
	s_add_i32 s0, s1, s33
	global_load_lds_dwordx4 v[186:187], off
	s_mov_b32 m0, s0
	v_lshl_add_u64 v[186:187], s[10:11], 0, v[190:191]
	global_load_lds_dwordx4 v[186:187], off
	s_add_i32 m0, s0, 0x2000
	v_lshl_add_u64 v[186:187], s[10:11], 0, v[180:181]
	global_load_lds_dwordx4 v[186:187], off
	s_mov_b32 m0, s55
	v_lshl_add_u64 v[186:187], v[222:223], 0, s[58:59]
	global_load_lds_dwordx4 v[186:187], off
	s_mov_b32 m0, s77
	v_lshl_add_u64 v[186:187], v[224:225], 0, s[58:59]
	global_load_lds_dwordx4 v[186:187], off
	s_waitcnt vmcnt(8) lgkmcnt(0)
	s_setprio 1
	s_barrier
	v_mfma_f32_16x16x32_bf16 v[88:91], v[128:131], v[160:163], v[88:91]
	v_mfma_f32_16x16x32_bf16 v[20:23], v[136:139], v[160:163], v[20:23]
	v_mfma_f32_16x16x32_bf16 v[92:95], v[128:131], v[168:171], v[92:95]
	v_mfma_f32_16x16x32_bf16 v[28:31], v[136:139], v[168:171], v[28:31]
	v_mfma_f32_16x16x32_bf16 v[80:83], v[128:131], v[196:199], v[80:83]
	v_mfma_f32_16x16x32_bf16 v[16:19], v[136:139], v[196:199], v[16:19]
	v_mfma_f32_16x16x32_bf16 v[76:79], v[128:131], v[212:215], v[76:79]
	v_mfma_f32_16x16x32_bf16 v[12:15], v[136:139], v[212:215], v[12:15]
	v_mfma_f32_16x16x32_bf16 v[88:91], v[132:135], v[164:167], v[88:91]
	v_mfma_f32_16x16x32_bf16 v[20:23], v[140:143], v[164:167], v[20:23]
	v_mfma_f32_16x16x32_bf16 v[92:95], v[132:135], v[172:175], v[92:95]
	v_mfma_f32_16x16x32_bf16 v[28:31], v[140:143], v[172:175], v[28:31]
	v_mfma_f32_16x16x32_bf16 v[80:83], v[132:135], v[208:211], v[80:83]
	v_mfma_f32_16x16x32_bf16 v[16:19], v[140:143], v[208:211], v[16:19]
	v_mfma_f32_16x16x32_bf16 v[76:79], v[132:135], v[216:219], v[76:79]
	v_mfma_f32_16x16x32_bf16 v[12:15], v[140:143], v[216:219], v[12:15]
	s_setprio 0
	s_setprio 1
	v_mfma_f32_16x16x32_bf16 v[68:71], v[144:147], v[160:163], v[68:71]
	v_mfma_f32_16x16x32_bf16 v[4:7], v[152:155], v[160:163], v[4:7]
	v_mfma_f32_16x16x32_bf16 v[84:87], v[144:147], v[168:171], v[84:87]
	v_mfma_f32_16x16x32_bf16 v[24:27], v[152:155], v[168:171], v[24:27]
	v_mfma_f32_16x16x32_bf16 v[72:75], v[144:147], v[196:199], v[72:75]
	v_mfma_f32_16x16x32_bf16 v[8:11], v[152:155], v[196:199], v[8:11]
	v_mfma_f32_16x16x32_bf16 v[64:67], v[144:147], v[212:215], v[64:67]
	v_mfma_f32_16x16x32_bf16 v[0:3], v[152:155], v[212:215], v[0:3]
	v_mfma_f32_16x16x32_bf16 v[68:71], v[148:151], v[164:167], v[68:71]
	v_mfma_f32_16x16x32_bf16 v[4:7], v[156:159], v[164:167], v[4:7]
	v_mfma_f32_16x16x32_bf16 v[84:87], v[148:151], v[172:175], v[84:87]
	v_mfma_f32_16x16x32_bf16 v[24:27], v[156:159], v[172:175], v[24:27]
	v_mfma_f32_16x16x32_bf16 v[72:75], v[148:151], v[208:211], v[72:75]
	v_mfma_f32_16x16x32_bf16 v[8:11], v[156:159], v[208:211], v[8:11]
	v_mfma_f32_16x16x32_bf16 v[64:67], v[148:151], v[216:219], v[64:67]
	v_mfma_f32_16x16x32_bf16 v[0:3], v[156:159], v[216:219], v[0:3]
	s_barrier
	s_setprio 0
	s_add_i32 vcc_lo, vcc_lo, 2
	s_add_u32 s66, s66, 0x100
	s_addc_u32 s67, s67, 0
	s_cmp_gt_u32 vcc_lo, 29
	s_mov_b64 s[10:11], s[16:17]
	s_cbranch_scc0 .LBB0_1105

.LBB0_1350:
	s_add_u32 s20, s16, 0x100
	s_addc_u32 s21, s17, 0
	s_add_i32 s0, 0, 0x10000
	s_cmpk_eq_i32 s53, 0x54
	s_cselect_b32 s25, s13, s21
	s_cselect_b32 s24, s12, s20
	s_cselect_b32 s23, s15, s52
	s_cselect_b32 s22, s14, s47
	s_add_i32 s1, 0, 0x14000
	v_add_u32_e32 v154, s0, v139
	v_add_u32_e32 v170, s1, v139
	ds_read_b128 v[142:145], v154
	ds_read_b128 v[146:149], v154 offset:1024
	ds_read_b128 v[150:153], v154 offset:2048
	ds_read_b128 v[154:157], v154 offset:3072
	ds_read_b128 v[158:161], v170
	ds_read_b128 v[162:165], v170 offset:1024
	ds_read_b128 v[166:169], v170 offset:2048
	ds_read_b128 v[170:173], v170 offset:3072
	v_lshl_add_u64 v[186:187], s[16:17], 0, v[134:135]
	s_add_i32 m0, s29, 0xc000
	ds_read_b128 v[174:177], v141
	ds_read_b128 v[178:181], v141 offset:1024
	ds_read_b128 v[182:185], v141 offset:2048
	ds_read_b128 v[196:199], v141 offset:3072
	ds_read_b128 v[200:203], v141 offset:4096
	ds_read_b128 v[204:207], v141 offset:5120
	ds_read_b128 v[208:211], v141 offset:6144
	ds_read_b128 v[212:215], v141 offset:7168
	global_load_lds_dwordx4 v[186:187], off
	s_add_i32 m0, s29, 0xe000
	v_lshl_add_u64 v[186:187], s[16:17], 0, v[136:137]
	global_load_lds_dwordx4 v[186:187], off
	s_waitcnt vmcnt(8) lgkmcnt(0)
	s_setprio 1
	s_barrier
	v_mfma_f32_16x16x32_bf16 v[124:127], v[142:145], v[174:177], v[124:127]
	v_mfma_f32_16x16x32_bf16 v[120:123], v[150:153], v[174:177], v[120:123]
	v_mfma_f32_16x16x32_bf16 v[116:119], v[142:145], v[182:185], v[116:119]
	v_mfma_f32_16x16x32_bf16 v[112:115], v[150:153], v[182:185], v[112:115]
	v_mfma_f32_16x16x32_bf16 v[100:103], v[142:145], v[200:203], v[100:103]
	v_mfma_f32_16x16x32_bf16 v[96:99], v[150:153], v[200:203], v[96:99]
	v_mfma_f32_16x16x32_bf16 v[84:87], v[142:145], v[208:211], v[84:87]
	v_mfma_f32_16x16x32_bf16 v[80:83], v[150:153], v[208:211], v[80:83]
	v_mfma_f32_16x16x32_bf16 v[124:127], v[146:149], v[178:181], v[124:127]
	v_mfma_f32_16x16x32_bf16 v[120:123], v[154:157], v[178:181], v[120:123]
	v_mfma_f32_16x16x32_bf16 v[116:119], v[146:149], v[196:199], v[116:119]
	v_mfma_f32_16x16x32_bf16 v[112:115], v[154:157], v[196:199], v[112:115]
	v_mfma_f32_16x16x32_bf16 v[100:103], v[146:149], v[204:207], v[100:103]
	v_mfma_f32_16x16x32_bf16 v[96:99], v[154:157], v[204:207], v[96:99]
	v_mfma_f32_16x16x32_bf16 v[84:87], v[146:149], v[212:215], v[84:87]
	v_mfma_f32_16x16x32_bf16 v[80:83], v[154:157], v[212:215], v[80:83]
	s_setprio 0
	s_setprio 1
	v_mfma_f32_16x16x32_bf16 v[108:111], v[158:161], v[174:177], v[108:111]
	v_mfma_f32_16x16x32_bf16 v[104:107], v[166:169], v[174:177], v[104:107]
	v_mfma_f32_16x16x32_bf16 v[92:95], v[158:161], v[182:185], v[92:95]
	v_mfma_f32_16x16x32_bf16 v[88:91], v[166:169], v[182:185], v[88:91]
	v_mfma_f32_16x16x32_bf16 v[76:79], v[158:161], v[200:203], v[76:79]
	v_mfma_f32_16x16x32_bf16 v[72:75], v[166:169], v[200:203], v[72:75]
	v_mfma_f32_16x16x32_bf16 v[68:71], v[158:161], v[208:211], v[68:71]
	v_mfma_f32_16x16x32_bf16 v[64:67], v[166:169], v[208:211], v[64:67]
	v_mfma_f32_16x16x32_bf16 v[108:111], v[162:165], v[178:181], v[108:111]
	v_mfma_f32_16x16x32_bf16 v[104:107], v[170:173], v[178:181], v[104:107]
	v_mfma_f32_16x16x32_bf16 v[92:95], v[162:165], v[196:199], v[92:95]
	v_mfma_f32_16x16x32_bf16 v[88:91], v[170:173], v[196:199], v[88:91]
	v_mfma_f32_16x16x32_bf16 v[76:79], v[162:165], v[204:207], v[76:79]
	v_mfma_f32_16x16x32_bf16 v[72:75], v[170:173], v[204:207], v[72:75]
	v_mfma_f32_16x16x32_bf16 v[68:71], v[162:165], v[212:215], v[68:71]
	v_mfma_f32_16x16x32_bf16 v[64:67], v[170:173], v[212:215], v[64:67]
	s_barrier
	s_setprio 0
	s_add_i32 s0, s0, s28
	v_lshl_add_u64 v[186:187], s[22:23], 0, v[190:191]
	s_mov_b32 m0, s0
	ds_read_b128 v[174:177], v141 offset:16384
	ds_read_b128 v[178:181], v141 offset:17408
	ds_read_b128 v[182:185], v141 offset:18432
	ds_read_b128 v[196:199], v141 offset:19456
	ds_read_b128 v[200:203], v141 offset:20480
	ds_read_b128 v[204:207], v141 offset:21504
	ds_read_b128 v[208:211], v141 offset:22528
	ds_read_b128 v[212:215], v141 offset:23552
	global_load_lds_dwordx4 v[186:187], off
	s_add_i32 m0, s0, 0x2000
	s_add_u32 s16, s22, 0x160000
	v_lshl_add_u64 v[216:217], s[22:23], 0, v[132:133]
	s_addc_u32 s17, s23, 0
	s_add_i32 s0, s1, s28
	global_load_lds_dwordx4 v[216:217], off
	v_lshl_add_u64 v[218:219], s[16:17], 0, v[190:191]
	s_mov_b32 m0, s0
	v_lshl_add_u64 v[220:221], s[24:25], 0, v[130:131]
	global_load_lds_dwordx4 v[218:219], off
	s_add_i32 m0, s0, 0x2000
	v_lshl_add_u64 v[218:219], s[16:17], 0, v[132:133]
	global_load_lds_dwordx4 v[218:219], off
	s_mov_b32 m0, s29
	v_lshl_add_u64 v[218:219], s[24:25], 0, v[128:129]
	global_load_lds_dwordx4 v[218:219], off
	s_mov_b32 m0, s30
	s_nop 0
	global_load_lds_dwordx4 v[220:221], off
	s_waitcnt vmcnt(8) lgkmcnt(0)
	s_setprio 1
	s_barrier
	v_mfma_f32_16x16x32_bf16 v[60:63], v[142:145], v[174:177], v[60:63]
	v_mfma_f32_16x16x32_bf16 v[56:59], v[150:153], v[174:177], v[56:59]
	v_mfma_f32_16x16x32_bf16 v[52:55], v[142:145], v[182:185], v[52:55]
	v_mfma_f32_16x16x32_bf16 v[48:51], v[150:153], v[182:185], v[48:51]
	v_mfma_f32_16x16x32_bf16 v[36:39], v[142:145], v[200:203], v[36:39]
	v_mfma_f32_16x16x32_bf16 v[32:35], v[150:153], v[200:203], v[32:35]
	v_mfma_f32_16x16x32_bf16 v[20:23], v[142:145], v[208:211], v[20:23]
	v_mfma_f32_16x16x32_bf16 v[16:19], v[150:153], v[208:211], v[16:19]
	v_mfma_f32_16x16x32_bf16 v[60:63], v[146:149], v[178:181], v[60:63]
	v_mfma_f32_16x16x32_bf16 v[56:59], v[154:157], v[178:181], v[56:59]
	v_mfma_f32_16x16x32_bf16 v[52:55], v[146:149], v[196:199], v[52:55]
	v_mfma_f32_16x16x32_bf16 v[48:51], v[154:157], v[196:199], v[48:51]
	v_mfma_f32_16x16x32_bf16 v[36:39], v[146:149], v[204:207], v[36:39]
	v_mfma_f32_16x16x32_bf16 v[32:35], v[154:157], v[204:207], v[32:35]
	v_mfma_f32_16x16x32_bf16 v[20:23], v[146:149], v[212:215], v[20:23]
	v_mfma_f32_16x16x32_bf16 v[16:19], v[154:157], v[212:215], v[16:19]
	s_setprio 0
	s_setprio 1
	v_mfma_f32_16x16x32_bf16 v[44:47], v[158:161], v[174:177], v[44:47]
	v_mfma_f32_16x16x32_bf16 v[40:43], v[166:169], v[174:177], v[40:43]
	v_mfma_f32_16x16x32_bf16 v[28:31], v[158:161], v[182:185], v[28:31]
	v_mfma_f32_16x16x32_bf16 v[24:27], v[166:169], v[182:185], v[24:27]
	v_mfma_f32_16x16x32_bf16 v[12:15], v[158:161], v[200:203], v[12:15]
	v_mfma_f32_16x16x32_bf16 v[8:11], v[166:169], v[200:203], v[8:11]
	v_mfma_f32_16x16x32_bf16 v[4:7], v[158:161], v[208:211], v[4:7]
	v_mfma_f32_16x16x32_bf16 v[0:3], v[166:169], v[208:211], v[0:3]
	v_mfma_f32_16x16x32_bf16 v[44:47], v[162:165], v[178:181], v[44:47]
	v_mfma_f32_16x16x32_bf16 v[40:43], v[170:173], v[178:181], v[40:43]
	v_mfma_f32_16x16x32_bf16 v[28:31], v[162:165], v[196:199], v[28:31]
	v_mfma_f32_16x16x32_bf16 v[24:27], v[170:173], v[196:199], v[24:27]
	v_mfma_f32_16x16x32_bf16 v[12:15], v[162:165], v[204:207], v[12:15]
	v_mfma_f32_16x16x32_bf16 v[8:11], v[170:173], v[204:207], v[8:11]
	v_mfma_f32_16x16x32_bf16 v[4:7], v[162:165], v[212:215], v[4:7]
	v_mfma_f32_16x16x32_bf16 v[0:3], v[170:173], v[212:215], v[0:3]
	s_barrier
	s_setprio 0
	s_add_i32 s0, 0, 0x18000
	s_add_i32 s1, 0, 0x1c000
	v_add_u32_e32 v154, s0, v139
	v_add_u32_e32 v170, s1, v139
	ds_read_b128 v[142:145], v154
	ds_read_b128 v[146:149], v154 offset:1024
	ds_read_b128 v[150:153], v154 offset:2048
	ds_read_b128 v[154:157], v154 offset:3072
	ds_read_b128 v[158:161], v170
	ds_read_b128 v[162:165], v170 offset:1024
	ds_read_b128 v[166:169], v170 offset:2048
	ds_read_b128 v[170:173], v170 offset:3072
	s_add_u32 s16, s24, 0x160000
	s_addc_u32 s17, s25, 0
	s_mov_b32 m0, s31
	v_lshl_add_u64 v[222:223], s[16:17], 0, v[128:129]
	ds_read_b128 v[174:177], v141 offset:32768
	ds_read_b128 v[178:181], v141 offset:33792
	ds_read_b128 v[182:185], v141 offset:34816
	ds_read_b128 v[196:199], v141 offset:35840
	ds_read_b128 v[200:203], v141 offset:36864
	ds_read_b128 v[204:207], v141 offset:37888
	ds_read_b128 v[208:211], v141 offset:38912
	ds_read_b128 v[212:215], v141 offset:39936
	global_load_lds_dwordx4 v[222:223], off
	s_mov_b32 m0, s33
	v_lshl_add_u64 v[222:223], s[16:17], 0, v[130:131]
	global_load_lds_dwordx4 v[222:223], off
	s_waitcnt vmcnt(8) lgkmcnt(0)
	s_setprio 1
	s_barrier
	v_mfma_f32_16x16x32_bf16 v[124:127], v[142:145], v[174:177], v[124:127]
	v_mfma_f32_16x16x32_bf16 v[120:123], v[150:153], v[174:177], v[120:123]
	v_mfma_f32_16x16x32_bf16 v[116:119], v[142:145], v[182:185], v[116:119]
	v_mfma_f32_16x16x32_bf16 v[112:115], v[150:153], v[182:185], v[112:115]
	v_mfma_f32_16x16x32_bf16 v[100:103], v[142:145], v[200:203], v[100:103]
	v_mfma_f32_16x16x32_bf16 v[96:99], v[150:153], v[200:203], v[96:99]
	v_mfma_f32_16x16x32_bf16 v[84:87], v[142:145], v[208:211], v[84:87]
	v_mfma_f32_16x16x32_bf16 v[80:83], v[150:153], v[208:211], v[80:83]
	v_mfma_f32_16x16x32_bf16 v[124:127], v[146:149], v[178:181], v[124:127]
	v_mfma_f32_16x16x32_bf16 v[120:123], v[154:157], v[178:181], v[120:123]
	v_mfma_f32_16x16x32_bf16 v[116:119], v[146:149], v[196:199], v[116:119]
	v_mfma_f32_16x16x32_bf16 v[112:115], v[154:157], v[196:199], v[112:115]
	v_mfma_f32_16x16x32_bf16 v[100:103], v[146:149], v[204:207], v[100:103]
	v_mfma_f32_16x16x32_bf16 v[96:99], v[154:157], v[204:207], v[96:99]
	v_mfma_f32_16x16x32_bf16 v[84:87], v[146:149], v[212:215], v[84:87]
	v_mfma_f32_16x16x32_bf16 v[80:83], v[154:157], v[212:215], v[80:83]
	s_setprio 0
	s_setprio 1
	v_mfma_f32_16x16x32_bf16 v[108:111], v[158:161], v[174:177], v[108:111]
	v_mfma_f32_16x16x32_bf16 v[104:107], v[166:169], v[174:177], v[104:107]
	v_mfma_f32_16x16x32_bf16 v[92:95], v[158:161], v[182:185], v[92:95]
	v_mfma_f32_16x16x32_bf16 v[88:91], v[166:169], v[182:185], v[88:91]
	v_mfma_f32_16x16x32_bf16 v[76:79], v[158:161], v[200:203], v[76:79]
	v_mfma_f32_16x16x32_bf16 v[72:75], v[166:169], v[200:203], v[72:75]
	v_mfma_f32_16x16x32_bf16 v[68:71], v[158:161], v[208:211], v[68:71]
	v_mfma_f32_16x16x32_bf16 v[64:67], v[166:169], v[208:211], v[64:67]
	v_mfma_f32_16x16x32_bf16 v[108:111], v[162:165], v[178:181], v[108:111]
	v_mfma_f32_16x16x32_bf16 v[104:107], v[170:173], v[178:181], v[104:107]
	v_mfma_f32_16x16x32_bf16 v[92:95], v[162:165], v[196:199], v[92:95]
	v_mfma_f32_16x16x32_bf16 v[88:91], v[170:173], v[196:199], v[88:91]
	v_mfma_f32_16x16x32_bf16 v[76:79], v[162:165], v[204:207], v[76:79]
	v_mfma_f32_16x16x32_bf16 v[72:75], v[170:173], v[204:207], v[72:75]
	v_mfma_f32_16x16x32_bf16 v[68:71], v[162:165], v[212:215], v[68:71]
	v_mfma_f32_16x16x32_bf16 v[64:67], v[170:173], v[212:215], v[64:67]
	s_barrier
	s_setprio 0
	s_add_i32 s0, s0, s28
	v_lshl_add_u64 v[186:187], v[186:187], 0, s[58:59]
	s_mov_b32 m0, s0
	ds_read_b128 v[174:177], v141 offset:49152
	ds_read_b128 v[178:181], v141 offset:50176
	ds_read_b128 v[182:185], v141 offset:51200
	ds_read_b128 v[196:199], v141 offset:52224
	ds_read_b128 v[200:203], v141 offset:53248
	ds_read_b128 v[204:207], v141 offset:54272
	ds_read_b128 v[208:211], v141 offset:55296
	ds_read_b128 v[212:215], v141 offset:56320
	global_load_lds_dwordx4 v[186:187], off
	s_add_i32 m0, s0, 0x2000
	s_add_u32 s16, s22, 0x160080
	v_lshl_add_u64 v[186:187], v[216:217], 0, s[58:59]
	s_addc_u32 s17, s23, 0
	s_add_i32 s0, s1, s28
	global_load_lds_dwordx4 v[186:187], off
	s_mov_b32 m0, s0
	v_lshl_add_u64 v[186:187], s[16:17], 0, v[190:191]
	global_load_lds_dwordx4 v[186:187], off
	s_add_i32 m0, s0, 0x2000
	v_lshl_add_u64 v[186:187], s[16:17], 0, v[132:133]
	global_load_lds_dwordx4 v[186:187], off
	s_mov_b32 m0, s37
	v_lshl_add_u64 v[186:187], v[218:219], 0, s[58:59]
	global_load_lds_dwordx4 v[186:187], off
	s_mov_b32 m0, s38
	v_lshl_add_u64 v[186:187], v[220:221], 0, s[58:59]
	global_load_lds_dwordx4 v[186:187], off
	s_waitcnt vmcnt(8) lgkmcnt(0)
	s_setprio 1
	s_barrier
	v_mfma_f32_16x16x32_bf16 v[60:63], v[142:145], v[174:177], v[60:63]
	v_mfma_f32_16x16x32_bf16 v[56:59], v[150:153], v[174:177], v[56:59]
	v_mfma_f32_16x16x32_bf16 v[52:55], v[142:145], v[182:185], v[52:55]
	v_mfma_f32_16x16x32_bf16 v[48:51], v[150:153], v[182:185], v[48:51]
	v_mfma_f32_16x16x32_bf16 v[36:39], v[142:145], v[200:203], v[36:39]
	v_mfma_f32_16x16x32_bf16 v[32:35], v[150:153], v[200:203], v[32:35]
	v_mfma_f32_16x16x32_bf16 v[20:23], v[142:145], v[208:211], v[20:23]
	v_mfma_f32_16x16x32_bf16 v[16:19], v[150:153], v[208:211], v[16:19]
	v_mfma_f32_16x16x32_bf16 v[60:63], v[146:149], v[178:181], v[60:63]
	v_mfma_f32_16x16x32_bf16 v[56:59], v[154:157], v[178:181], v[56:59]
	v_mfma_f32_16x16x32_bf16 v[52:55], v[146:149], v[196:199], v[52:55]
	v_mfma_f32_16x16x32_bf16 v[48:51], v[154:157], v[196:199], v[48:51]
	v_mfma_f32_16x16x32_bf16 v[36:39], v[146:149], v[204:207], v[36:39]
	v_mfma_f32_16x16x32_bf16 v[32:35], v[154:157], v[204:207], v[32:35]
	v_mfma_f32_16x16x32_bf16 v[20:23], v[146:149], v[212:215], v[20:23]
	v_mfma_f32_16x16x32_bf16 v[16:19], v[154:157], v[212:215], v[16:19]
	s_setprio 0
	s_setprio 1
	v_mfma_f32_16x16x32_bf16 v[44:47], v[158:161], v[174:177], v[44:47]
	v_mfma_f32_16x16x32_bf16 v[40:43], v[166:169], v[174:177], v[40:43]
	v_mfma_f32_16x16x32_bf16 v[28:31], v[158:161], v[182:185], v[28:31]
	v_mfma_f32_16x16x32_bf16 v[24:27], v[166:169], v[182:185], v[24:27]
	v_mfma_f32_16x16x32_bf16 v[12:15], v[158:161], v[200:203], v[12:15]
	v_mfma_f32_16x16x32_bf16 v[8:11], v[166:169], v[200:203], v[8:11]
	v_mfma_f32_16x16x32_bf16 v[4:7], v[158:161], v[208:211], v[4:7]
	v_mfma_f32_16x16x32_bf16 v[0:3], v[166:169], v[208:211], v[0:3]
	v_mfma_f32_16x16x32_bf16 v[44:47], v[162:165], v[178:181], v[44:47]
	v_mfma_f32_16x16x32_bf16 v[40:43], v[170:173], v[178:181], v[40:43]
	v_mfma_f32_16x16x32_bf16 v[28:31], v[162:165], v[196:199], v[28:31]
	v_mfma_f32_16x16x32_bf16 v[24:27], v[170:173], v[196:199], v[24:27]
	v_mfma_f32_16x16x32_bf16 v[12:15], v[162:165], v[204:207], v[12:15]
	v_mfma_f32_16x16x32_bf16 v[8:11], v[170:173], v[204:207], v[8:11]
	v_mfma_f32_16x16x32_bf16 v[4:7], v[162:165], v[212:215], v[4:7]
	v_mfma_f32_16x16x32_bf16 v[0:3], v[170:173], v[212:215], v[0:3]
	s_barrier
	s_setprio 0
	s_add_i32 s53, s53, 2
	s_add_u32 s47, s47, 0x100
	s_addc_u32 s52, s52, 0
	s_cmpk_gt_u32 s53, 0x55
	s_mov_b64 s[16:17], s[20:21]
	s_cbranch_scc0 .LBB0_1350
